# tile boundary: trailing wave half takes its realign barrier after the tile head instead of before it (head overlaps the leading half's head + first segment)
# baseline (speedup 1.0000x reference)
.LBB0_69:
	v_bfe_u32 v147, v208, 4, 2
	v_lshlrev_b32_e32 v16, 6, v143
	v_lshlrev_b32_e32 v17, 2, v143
	s_and_b32 s22, s6, 3
	v_lshl_or_b32 v16, v147, 4, v16
	s_lshl_b32 s6, s15, 13
	v_and_b32_e32 v17, 32, v17
	s_add_i32 m0, s18, 0x18000
	v_lshl_add_u64 v[8:9], v[8:9], 0, s[34:35]
	v_bitop3_b32 v18, s6, v16, v17 bitop3:0xf6
	s_lshl_b32 s6, s22, 12
	s_waitcnt vmcnt(2)
	s_barrier
	global_load_lds_dwordx4 v[8:9], off
	v_lshl_add_u64 v[6:7], v[6:7], 0, s[34:35]
	s_add_i32 m0, s18, 0x1a000
	s_add_i32 s23, s18, 0x8000
	s_add_i32 s29, s18, 0xa000
	s_sext_i32_i8 s83, s38
	global_load_lds_dwordx4 v[6:7], off
	v_lshl_add_u64 v[2:3], v[2:3], 0, s[34:35]
	s_mov_b32 m0, s23
	s_add_u32 s38, s92, 0x40080
	global_load_lds_dwordx4 v[2:3], off
	v_lshl_add_u64 v[2:3], v[4:5], 0, s[34:35]
	s_mov_b32 m0, s29
	s_addc_u32 s39, s93, 0
	global_load_lds_dwordx4 v[2:3], off
	s_add_i32 m0, s18, 0x1c000
	v_lshl_add_u64 v[2:3], s[38:39], 0, v[0:1]
	global_load_lds_dwordx4 v[2:3], off
	v_lshl_add_u64 v[2:3], s[38:39], 0, v[130:131]
	s_add_i32 m0, s18, 0x1e000
	s_cmpk_lt_u32 s2, 0x100
	global_load_lds_dwordx4 v[2:3], off
	v_lshlrev_b32_e32 v2, 14, v14
	v_and_b32_e32 v2, 0xffff8000, v2
	v_lshl_add_u32 v2, v13, 11, v2
	v_and_b32_e32 v3, 1, v14
	v_lshl_or_b32 v2, v3, 6, v2
	v_lshl_add_u32 v136, v15, 1, v2
	v_lshlrev_b32_e32 v2, 14, v10
	v_and_b32_e32 v2, 0xffff8000, v2
	s_waitcnt vmcnt(6)
	v_lshl_add_u32 v2, v11, 11, v2
	v_and_b32_e32 v3, 1, v10
	v_lshl_or_b32 v2, v3, 6, v2
	v_bitop3_b32 v151, s6, v16, v17 bitop3:0xf6
	s_cselect_b64 s[46:47], -1, 0
	s_ashr_i32 s48, s12, 31
	v_mov_b32_e32 v137, v1
	v_lshl_add_u32 v138, v12, 1, v2
	v_mov_b32_e32 v139, v1
	s_mov_b32 s81, 0
	v_add_u32_e32 v153, 0, v18
	s_barrier
	s_mov_b32 s52, 0
	s_branch .LBB0_72
.Lzskip_gin:
	v_mov_b64_e32 v[18:19], 0
	v_mov_b64_e32 v[20:21], 0
	v_mov_b64_e32 v[22:23], 0
	v_mov_b64_e32 v[24:25], 0
	v_mov_b64_e32 v[26:27], 0
	v_mov_b64_e32 v[28:29], 0
	v_mov_b64_e32 v[30:31], 0
	v_mov_b64_e32 v[32:33], 0
	v_mov_b64_e32 v[34:35], 0
	v_mov_b64_e32 v[36:37], 0
	v_mov_b64_e32 v[38:39], 0
	v_mov_b64_e32 v[40:41], 0
	v_mov_b64_e32 v[42:43], 0
	v_mov_b64_e32 v[44:45], 0
	v_mov_b64_e32 v[46:47], 0
	v_mov_b64_e32 v[48:49], 0
	v_mov_b64_e32 v[50:51], 0
	v_mov_b64_e32 v[52:53], 0
	v_mov_b64_e32 v[54:55], 0
	v_mov_b64_e32 v[56:57], 0
	v_mov_b64_e32 v[58:59], 0
	v_mov_b64_e32 v[60:61], 0
	s_branch .LBB0_74
	s_nop 0
	s_nop 0
	s_nop 0
	s_nop 0
	s_nop 0
	s_nop 0
	s_nop 0
	s_nop 0
	s_nop 0
	s_nop 0
	s_nop 0
	s_nop 0
	s_nop 0
	s_nop 0
	s_nop 0
	s_nop 0
	s_nop 0
	s_nop 0
	s_nop 0
	s_nop 0
	s_nop 0
	s_nop 0
	s_nop 0
	s_nop 0
	s_nop 0
	s_nop 0
	s_nop 0
	s_nop 0
	s_nop 0
	s_nop 0
	s_nop 0
	s_nop 0

.LBB0_74:
	s_ashr_i32 s63, s62, 31
	v_mov_b64_e32 v[62:63], 0
	s_lshl_b64 s[68:69], s[62:63], 19
	v_mov_b64_e32 v[64:65], 0
	s_add_u32 s76, s36, s68
	v_mov_b64_e32 v[66:67], 0
	s_addc_u32 s77, s37, s69
	v_mov_b64_e32 v[68:69], 0
	s_and_b64 s[68:69], s[38:39], exec
	v_mov_b64_e32 v[70:71], 0
	s_cselect_b32 s2, s77, s91
	v_mov_b64_e32 v[72:73], 0
	s_cselect_b32 s6, s76, s90
	v_mov_b64_e32 v[74:75], 0
	s_ashr_i32 s51, s50, 31
	v_mov_b64_e32 v[76:77], 0
	s_lshl_b64 s[68:69], s[50:51], 19
	v_mov_b64_e32 v[78:79], 0
	s_add_u32 s78, s42, s68
	v_mov_b64_e32 v[80:81], 0
	s_addc_u32 s79, s43, s69
	v_mov_b64_e32 v[82:83], 0
	s_and_b64 s[68:69], s[38:39], exec
	v_mov_b64_e32 v[84:85], 0
	s_cselect_b32 s51, s79, s93
	v_mov_b64_e32 v[86:87], 0
	s_cselect_b32 s63, s78, s92
	v_mov_b64_e32 v[88:89], 0
	s_add_u32 s90, s90, 0x40080
	v_mov_b64_e32 v[90:91], 0
	s_addc_u32 s91, s91, 0
	v_mov_b64_e32 v[92:93], 0
	s_add_u32 s89, s92, 0x100
	v_mov_b64_e32 v[94:95], 0
	v_mov_b64_e32 v[2:3], 0
	v_mov_b64_e32 v[96:97], 0
	v_mov_b64_e32 v[98:99], 0
	v_mov_b64_e32 v[100:101], 0
	v_mov_b64_e32 v[102:103], 0
	v_mov_b64_e32 v[104:105], 0
	v_mov_b64_e32 v[106:107], 0
	v_mov_b64_e32 v[108:109], 0
	v_mov_b64_e32 v[110:111], 0
	v_mov_b64_e32 v[112:113], 0
	v_mov_b64_e32 v[114:115], 0
	v_mov_b64_e32 v[116:117], 0
	v_mov_b64_e32 v[118:119], 0
	v_mov_b64_e32 v[120:121], 0
	v_mov_b64_e32 v[122:123], 0
	v_mov_b64_e32 v[124:125], 0
	v_mov_b64_e32 v[126:127], 0
	v_mov_b64_e32 v[128:129], 0
	s_addc_u32 s96, s93, 0
	s_mov_b32 s97, -2
	s_cmp_eq_u32 s52, 0
	s_cbranch_scc1 .Lrb_gin
	s_mov_b32 s52, 0
	s_barrier
.Lrb_gin:
.LBB0_75:
	s_add_u32 s68, s90, 0xfffc0080
	s_addc_u32 s69, s91, -1
	s_add_i32 s70, 0, 0x10000
	s_cmp_eq_u32 s97, 12
	s_cselect_b32 s95, s2, s69
	s_cselect_b32 s94, s6, s68
	v_add_u32_e32 v140, s70, v151
	s_cselect_b32 s93, s51, s96
	s_cselect_b32 s92, s63, s89
	s_add_i32 s71, 0, 0x14000
	s_waitcnt vmcnt(0)
	ds_read_b128 v[154:157], v140
	ds_read_b128 v[158:161], v140 offset:1024
	ds_read_b128 v[162:165], v140 offset:2048
	ds_read_b128 v[166:169], v140 offset:3072
	v_add_u32_e32 v140, s71, v151
	ds_read_b128 v[170:173], v140
	ds_read_b128 v[174:177], v140 offset:1024
	ds_read_b128 v[178:181], v140 offset:2048
	ds_read_b128 v[182:185], v140 offset:3072
	v_lshl_add_u64 v[140:141], s[90:91], 0, v[136:137]
	s_add_i32 m0, s18, 0xc000
	ds_read_b128 v[186:189], v153
	ds_read_b128 v[190:193], v153 offset:1024
	ds_read_b128 v[194:197], v153 offset:2048
	ds_read_b128 v[198:201], v153 offset:3072
	ds_read_b128 v[202:205], v153 offset:4096
	ds_read_b128 v[210:213], v153 offset:5120
	ds_read_b128 v[214:217], v153 offset:6144
	ds_read_b128 v[218:221], v153 offset:7168
	global_load_lds_dwordx4 v[140:141], off
	v_lshl_add_u64 v[140:141], s[90:91], 0, v[138:139]
	s_add_i32 m0, s18, 0xe000
	s_nop 0
	global_load_lds_dwordx4 v[140:141], off
	s_waitcnt vmcnt(8)
	s_waitcnt lgkmcnt(0)
	s_barrier
	s_waitcnt lgkmcnt(0)
	v_mfma_f32_16x16x32_bf16 v[126:129], v[154:157], v[186:189], v[126:129]
	v_mfma_f32_16x16x32_bf16 v[122:125], v[162:165], v[186:189], v[122:125]
	v_mfma_f32_16x16x32_bf16 v[110:113], v[154:157], v[194:197], v[110:113]
	v_mfma_f32_16x16x32_bf16 v[106:109], v[162:165], v[194:197], v[106:109]
	v_mfma_f32_16x16x32_bf16 v[98:101], v[154:157], v[202:205], v[98:101]
	v_mfma_f32_16x16x32_bf16 v[90:93], v[162:165], v[202:205], v[90:93]
	v_mfma_f32_16x16x32_bf16 v[82:85], v[154:157], v[214:217], v[82:85]
	v_mfma_f32_16x16x32_bf16 v[74:77], v[162:165], v[214:217], v[74:77]
	v_mfma_f32_16x16x32_bf16 v[118:121], v[170:173], v[186:189], v[118:121]
	v_mfma_f32_16x16x32_bf16 v[114:117], v[178:181], v[186:189], v[114:117]
	v_mfma_f32_16x16x32_bf16 v[102:105], v[170:173], v[194:197], v[102:105]
	v_mfma_f32_16x16x32_bf16 v[94:97], v[178:181], v[194:197], v[94:97]
	v_mfma_f32_16x16x32_bf16 v[86:89], v[170:173], v[202:205], v[86:89]
	v_mfma_f32_16x16x32_bf16 v[78:81], v[178:181], v[202:205], v[78:81]
	v_mfma_f32_16x16x32_bf16 v[70:73], v[170:173], v[214:217], v[70:73]
	v_mfma_f32_16x16x32_bf16 v[66:69], v[178:181], v[214:217], v[66:69]
	v_mfma_f32_16x16x32_bf16 v[126:129], v[158:161], v[190:193], v[126:129]
	v_mfma_f32_16x16x32_bf16 v[122:125], v[166:169], v[190:193], v[122:125]
	v_mfma_f32_16x16x32_bf16 v[110:113], v[158:161], v[198:201], v[110:113]
	v_mfma_f32_16x16x32_bf16 v[106:109], v[166:169], v[198:201], v[106:109]
	v_mfma_f32_16x16x32_bf16 v[98:101], v[158:161], v[210:213], v[98:101]
	v_mfma_f32_16x16x32_bf16 v[90:93], v[166:169], v[210:213], v[90:93]
	v_mfma_f32_16x16x32_bf16 v[82:85], v[158:161], v[218:221], v[82:85]
	v_mfma_f32_16x16x32_bf16 v[74:77], v[166:169], v[218:221], v[74:77]
	v_mfma_f32_16x16x32_bf16 v[118:121], v[174:177], v[190:193], v[118:121]
	v_mfma_f32_16x16x32_bf16 v[114:117], v[182:185], v[190:193], v[114:117]
	v_mfma_f32_16x16x32_bf16 v[102:105], v[174:177], v[198:201], v[102:105]
	v_mfma_f32_16x16x32_bf16 v[94:97], v[182:185], v[198:201], v[94:97]
	v_mfma_f32_16x16x32_bf16 v[86:89], v[174:177], v[210:213], v[86:89]
	v_mfma_f32_16x16x32_bf16 v[78:81], v[182:185], v[210:213], v[78:81]
	v_mfma_f32_16x16x32_bf16 v[70:73], v[174:177], v[218:221], v[70:73]
	v_mfma_f32_16x16x32_bf16 v[66:69], v[182:185], v[218:221], v[66:69]
	s_barrier
	s_add_i32 s68, s70, s16
	v_lshl_add_u64 v[140:141], s[92:93], 0, v[0:1]
	s_mov_b32 m0, s68
	ds_read_b128 v[186:189], v153 offset:16384
	ds_read_b128 v[190:193], v153 offset:17408
	ds_read_b128 v[194:197], v153 offset:18432
	ds_read_b128 v[198:201], v153 offset:19456
	ds_read_b128 v[202:205], v153 offset:20480
	ds_read_b128 v[210:213], v153 offset:21504
	ds_read_b128 v[214:217], v153 offset:22528
	ds_read_b128 v[218:221], v153 offset:23552
	global_load_lds_dwordx4 v[140:141], off
	s_add_i32 m0, s68, 0x2000
	s_add_u32 s68, s92, 0x40000
	v_lshl_add_u64 v[144:145], s[92:93], 0, v[130:131]
	s_addc_u32 s69, s93, 0
	s_add_i32 s70, s71, s16
	global_load_lds_dwordx4 v[144:145], off
	v_lshl_add_u64 v[148:149], s[68:69], 0, v[0:1]
	s_mov_b32 m0, s70
	v_lshl_add_u64 v[206:207], s[94:95], 0, v[132:133]
	global_load_lds_dwordx4 v[148:149], off
	v_lshl_add_u64 v[148:149], s[68:69], 0, v[130:131]
	s_add_i32 m0, s70, 0x2000
	s_nop 0
	global_load_lds_dwordx4 v[148:149], off
	v_lshl_add_u64 v[148:149], s[94:95], 0, v[134:135]
	s_mov_b32 m0, s18
	s_nop 0
	global_load_lds_dwordx4 v[148:149], off
	s_mov_b32 m0, s19
	s_nop 0
	global_load_lds_dwordx4 v[206:207], off
	s_waitcnt vmcnt(8)
	s_waitcnt lgkmcnt(0)
	s_barrier
	s_waitcnt lgkmcnt(0)
	v_mfma_f32_16x16x32_bf16 v[62:65], v[154:157], v[186:189], v[62:65]
	v_mfma_f32_16x16x32_bf16 v[58:61], v[162:165], v[186:189], v[58:61]
	v_mfma_f32_16x16x32_bf16 v[50:53], v[154:157], v[194:197], v[50:53]
	v_mfma_f32_16x16x32_bf16 v[42:45], v[162:165], v[194:197], v[42:45]
	v_mfma_f32_16x16x32_bf16 v[34:37], v[154:157], v[202:205], v[34:37]
	v_mfma_f32_16x16x32_bf16 v[26:29], v[162:165], v[202:205], v[26:29]
	v_mfma_f32_16x16x32_bf16 v[18:21], v[154:157], v[214:217], v[18:21]
	v_mfma_f32_16x16x32_bf16 v[10:13], v[162:165], v[214:217], v[10:13]
	v_mfma_f32_16x16x32_bf16 v[54:57], v[170:173], v[186:189], v[54:57]
	v_mfma_f32_16x16x32_bf16 v[46:49], v[178:181], v[186:189], v[46:49]
	v_mfma_f32_16x16x32_bf16 v[38:41], v[170:173], v[194:197], v[38:41]
	v_mfma_f32_16x16x32_bf16 v[30:33], v[178:181], v[194:197], v[30:33]
	v_mfma_f32_16x16x32_bf16 v[22:25], v[170:173], v[202:205], v[22:25]
	v_mfma_f32_16x16x32_bf16 v[14:17], v[178:181], v[202:205], v[14:17]
	v_mfma_f32_16x16x32_bf16 v[6:9], v[170:173], v[214:217], v[6:9]
	v_mfma_f32_16x16x32_bf16 v[2:5], v[178:181], v[214:217], v[2:5]
	v_mfma_f32_16x16x32_bf16 v[62:65], v[158:161], v[190:193], v[62:65]
	v_mfma_f32_16x16x32_bf16 v[58:61], v[166:169], v[190:193], v[58:61]
	v_mfma_f32_16x16x32_bf16 v[50:53], v[158:161], v[198:201], v[50:53]
	v_mfma_f32_16x16x32_bf16 v[42:45], v[166:169], v[198:201], v[42:45]
	v_mfma_f32_16x16x32_bf16 v[34:37], v[158:161], v[210:213], v[34:37]
	v_mfma_f32_16x16x32_bf16 v[26:29], v[166:169], v[210:213], v[26:29]
	v_mfma_f32_16x16x32_bf16 v[18:21], v[158:161], v[218:221], v[18:21]
	v_mfma_f32_16x16x32_bf16 v[10:13], v[166:169], v[218:221], v[10:13]
	v_mfma_f32_16x16x32_bf16 v[54:57], v[174:177], v[190:193], v[54:57]
	v_mfma_f32_16x16x32_bf16 v[46:49], v[182:185], v[190:193], v[46:49]
	v_mfma_f32_16x16x32_bf16 v[38:41], v[174:177], v[198:201], v[38:41]
	v_mfma_f32_16x16x32_bf16 v[30:33], v[182:185], v[198:201], v[30:33]
	v_mfma_f32_16x16x32_bf16 v[22:25], v[174:177], v[210:213], v[22:25]
	v_mfma_f32_16x16x32_bf16 v[14:17], v[182:185], v[210:213], v[14:17]
	v_mfma_f32_16x16x32_bf16 v[6:9], v[174:177], v[218:221], v[6:9]
	v_mfma_f32_16x16x32_bf16 v[2:5], v[182:185], v[218:221], v[2:5]
	s_barrier
	s_add_i32 s70, 0, 0x18000
	v_add_u32_e32 v142, s70, v151
	s_add_i32 s71, 0, 0x1c000
	ds_read_b128 v[154:157], v142
	ds_read_b128 v[158:161], v142 offset:1024
	ds_read_b128 v[162:165], v142 offset:2048
	ds_read_b128 v[166:169], v142 offset:3072
	v_add_u32_e32 v142, s71, v151
	ds_read_b128 v[170:173], v142
	ds_read_b128 v[174:177], v142 offset:1024
	ds_read_b128 v[178:181], v142 offset:2048
	ds_read_b128 v[182:185], v142 offset:3072
	s_add_u32 s68, s94, 0x40000
	s_addc_u32 s69, s95, 0
	s_mov_b32 m0, s20
	v_lshl_add_u64 v[222:223], s[68:69], 0, v[134:135]
	ds_read_b128 v[186:189], v153 offset:32768
	ds_read_b128 v[190:193], v153 offset:33792
	ds_read_b128 v[194:197], v153 offset:34816
	ds_read_b128 v[198:201], v153 offset:35840
	ds_read_b128 v[202:205], v153 offset:36864
	ds_read_b128 v[210:213], v153 offset:37888
	ds_read_b128 v[214:217], v153 offset:38912
	ds_read_b128 v[218:221], v153 offset:39936
	global_load_lds_dwordx4 v[222:223], off
	v_lshl_add_u64 v[222:223], s[68:69], 0, v[132:133]
	s_mov_b32 m0, s21
	s_nop 0
	global_load_lds_dwordx4 v[222:223], off
	s_waitcnt vmcnt(8)
	s_waitcnt lgkmcnt(0)
	s_barrier
	s_waitcnt lgkmcnt(0)
	v_mfma_f32_16x16x32_bf16 v[126:129], v[154:157], v[186:189], v[126:129]
	v_mfma_f32_16x16x32_bf16 v[122:125], v[162:165], v[186:189], v[122:125]
	v_mfma_f32_16x16x32_bf16 v[110:113], v[154:157], v[194:197], v[110:113]
	v_mfma_f32_16x16x32_bf16 v[106:109], v[162:165], v[194:197], v[106:109]
	v_mfma_f32_16x16x32_bf16 v[98:101], v[154:157], v[202:205], v[98:101]
	v_mfma_f32_16x16x32_bf16 v[90:93], v[162:165], v[202:205], v[90:93]
	v_mfma_f32_16x16x32_bf16 v[82:85], v[154:157], v[214:217], v[82:85]
	v_mfma_f32_16x16x32_bf16 v[74:77], v[162:165], v[214:217], v[74:77]
	v_mfma_f32_16x16x32_bf16 v[118:121], v[170:173], v[186:189], v[118:121]
	v_mfma_f32_16x16x32_bf16 v[114:117], v[178:181], v[186:189], v[114:117]
	v_mfma_f32_16x16x32_bf16 v[102:105], v[170:173], v[194:197], v[102:105]
	v_mfma_f32_16x16x32_bf16 v[94:97], v[178:181], v[194:197], v[94:97]
	v_mfma_f32_16x16x32_bf16 v[86:89], v[170:173], v[202:205], v[86:89]
	v_mfma_f32_16x16x32_bf16 v[78:81], v[178:181], v[202:205], v[78:81]
	v_mfma_f32_16x16x32_bf16 v[70:73], v[170:173], v[214:217], v[70:73]
	v_mfma_f32_16x16x32_bf16 v[66:69], v[178:181], v[214:217], v[66:69]
	v_mfma_f32_16x16x32_bf16 v[126:129], v[158:161], v[190:193], v[126:129]
	v_mfma_f32_16x16x32_bf16 v[122:125], v[166:169], v[190:193], v[122:125]
	v_mfma_f32_16x16x32_bf16 v[110:113], v[158:161], v[198:201], v[110:113]
	v_mfma_f32_16x16x32_bf16 v[106:109], v[166:169], v[198:201], v[106:109]
	v_mfma_f32_16x16x32_bf16 v[98:101], v[158:161], v[210:213], v[98:101]
	v_mfma_f32_16x16x32_bf16 v[90:93], v[166:169], v[210:213], v[90:93]
	v_mfma_f32_16x16x32_bf16 v[82:85], v[158:161], v[218:221], v[82:85]
	v_mfma_f32_16x16x32_bf16 v[74:77], v[166:169], v[218:221], v[74:77]
	v_mfma_f32_16x16x32_bf16 v[118:121], v[174:177], v[190:193], v[118:121]
	v_mfma_f32_16x16x32_bf16 v[114:117], v[182:185], v[190:193], v[114:117]
	v_mfma_f32_16x16x32_bf16 v[102:105], v[174:177], v[198:201], v[102:105]
	v_mfma_f32_16x16x32_bf16 v[94:97], v[182:185], v[198:201], v[94:97]
	v_mfma_f32_16x16x32_bf16 v[86:89], v[174:177], v[210:213], v[86:89]
	v_mfma_f32_16x16x32_bf16 v[78:81], v[182:185], v[210:213], v[78:81]
	v_mfma_f32_16x16x32_bf16 v[70:73], v[174:177], v[218:221], v[70:73]
	v_mfma_f32_16x16x32_bf16 v[66:69], v[182:185], v[218:221], v[66:69]
	s_barrier
	s_add_i32 s68, s70, s16
	v_lshl_add_u64 v[140:141], v[140:141], 0, s[34:35]
	s_mov_b32 m0, s68
	ds_read_b128 v[186:189], v153 offset:49152
	ds_read_b128 v[190:193], v153 offset:50176
	ds_read_b128 v[194:197], v153 offset:51200
	ds_read_b128 v[198:201], v153 offset:52224
	ds_read_b128 v[202:205], v153 offset:53248
	ds_read_b128 v[210:213], v153 offset:54272
	ds_read_b128 v[214:217], v153 offset:55296
	ds_read_b128 v[218:221], v153 offset:56320
	global_load_lds_dwordx4 v[140:141], off
	s_add_i32 m0, s68, 0x2000
	s_add_u32 s68, s92, 0x40080
	v_lshl_add_u64 v[140:141], v[144:145], 0, s[34:35]
	s_addc_u32 s69, s93, 0
	s_add_i32 s70, s71, s16
	global_load_lds_dwordx4 v[140:141], off
	v_lshl_add_u64 v[140:141], s[68:69], 0, v[0:1]
	s_mov_b32 m0, s70
	s_nop 0
	global_load_lds_dwordx4 v[140:141], off
	v_lshl_add_u64 v[140:141], s[68:69], 0, v[130:131]
	s_add_i32 m0, s70, 0x2000
	s_nop 0
	global_load_lds_dwordx4 v[140:141], off
	v_lshl_add_u64 v[140:141], v[148:149], 0, s[34:35]
	s_mov_b32 m0, s23
	s_nop 0
	global_load_lds_dwordx4 v[140:141], off
	v_lshl_add_u64 v[140:141], v[206:207], 0, s[34:35]
	s_mov_b32 m0, s29
	s_nop 0
	global_load_lds_dwordx4 v[140:141], off
	s_waitcnt vmcnt(8)
	s_waitcnt lgkmcnt(0)
	s_barrier
	s_waitcnt lgkmcnt(0)
	v_mfma_f32_16x16x32_bf16 v[62:65], v[154:157], v[186:189], v[62:65]
	v_mfma_f32_16x16x32_bf16 v[58:61], v[162:165], v[186:189], v[58:61]
	v_mfma_f32_16x16x32_bf16 v[50:53], v[154:157], v[194:197], v[50:53]
	v_mfma_f32_16x16x32_bf16 v[42:45], v[162:165], v[194:197], v[42:45]
	v_mfma_f32_16x16x32_bf16 v[34:37], v[154:157], v[202:205], v[34:37]
	v_mfma_f32_16x16x32_bf16 v[26:29], v[162:165], v[202:205], v[26:29]
	v_mfma_f32_16x16x32_bf16 v[18:21], v[154:157], v[214:217], v[18:21]
	v_mfma_f32_16x16x32_bf16 v[10:13], v[162:165], v[214:217], v[10:13]
	v_mfma_f32_16x16x32_bf16 v[54:57], v[170:173], v[186:189], v[54:57]
	v_mfma_f32_16x16x32_bf16 v[46:49], v[178:181], v[186:189], v[46:49]
	v_mfma_f32_16x16x32_bf16 v[38:41], v[170:173], v[194:197], v[38:41]
	v_mfma_f32_16x16x32_bf16 v[30:33], v[178:181], v[194:197], v[30:33]
	v_mfma_f32_16x16x32_bf16 v[22:25], v[170:173], v[202:205], v[22:25]
	v_mfma_f32_16x16x32_bf16 v[14:17], v[178:181], v[202:205], v[14:17]
	v_mfma_f32_16x16x32_bf16 v[6:9], v[170:173], v[214:217], v[6:9]
	v_mfma_f32_16x16x32_bf16 v[2:5], v[178:181], v[214:217], v[2:5]
	v_mfma_f32_16x16x32_bf16 v[62:65], v[158:161], v[190:193], v[62:65]
	v_mfma_f32_16x16x32_bf16 v[58:61], v[166:169], v[190:193], v[58:61]
	v_mfma_f32_16x16x32_bf16 v[50:53], v[158:161], v[198:201], v[50:53]
	v_mfma_f32_16x16x32_bf16 v[42:45], v[166:169], v[198:201], v[42:45]
	v_mfma_f32_16x16x32_bf16 v[34:37], v[158:161], v[210:213], v[34:37]
	v_mfma_f32_16x16x32_bf16 v[26:29], v[166:169], v[210:213], v[26:29]
	v_mfma_f32_16x16x32_bf16 v[18:21], v[158:161], v[218:221], v[18:21]
	v_mfma_f32_16x16x32_bf16 v[10:13], v[166:169], v[218:221], v[10:13]
	v_mfma_f32_16x16x32_bf16 v[54:57], v[174:177], v[190:193], v[54:57]
	v_mfma_f32_16x16x32_bf16 v[46:49], v[182:185], v[190:193], v[46:49]
	v_mfma_f32_16x16x32_bf16 v[38:41], v[174:177], v[198:201], v[38:41]
	v_mfma_f32_16x16x32_bf16 v[30:33], v[182:185], v[198:201], v[30:33]
	v_mfma_f32_16x16x32_bf16 v[22:25], v[174:177], v[210:213], v[22:25]
	v_mfma_f32_16x16x32_bf16 v[14:17], v[182:185], v[210:213], v[14:17]
	v_mfma_f32_16x16x32_bf16 v[6:9], v[174:177], v[218:221], v[6:9]
	v_mfma_f32_16x16x32_bf16 v[2:5], v[182:185], v[218:221], v[2:5]
	s_barrier
	s_add_i32 s97, s97, 2
	s_add_u32 s90, s90, 0x100
	s_addc_u32 s91, s91, 0
	s_add_u32 s89, s89, 0x100
	s_addc_u32 s96, s96, 0
	s_cmp_gt_u32 s97, 13
	s_cbranch_scc0 .LBB0_75
	s_and_b64 vcc, exec, s[46:47]
	s_cbranch_vccz .LBB0_78
	s_barrier

.LBB0_83:
	s_andn2_b64 vcc, exec, s[44:45]
	s_cbranch_vccnz .LBB0_70
	s_mov_b32 s52, 1
	s_branch .LBB0_70

.LBB0_174:
	s_and_b32 s23, s6, 3
	s_lshr_b32 s29, s15, 6
	s_lshl_b32 s6, s16, 13
	s_lshl_b32 s38, s23, 12
	s_add_u32 s76, s24, 0x196a0400
	s_addc_u32 s77, s25, 0
	s_add_i32 m0, s19, 0x18000
	v_lshl_add_u64 v[2:3], v[2:3], 0, s[34:35]
	s_waitcnt vmcnt(2)
	s_barrier
	global_load_lds_dwordx4 v[2:3], off
	v_lshl_add_u64 v[2:3], v[4:5], 0, s[34:35]
	s_add_i32 m0, s19, 0x1a000
	s_add_i32 s81, s19, 0x8000
	global_load_lds_dwordx4 v[2:3], off
	v_lshl_add_u64 v[2:3], v[10:11], 0, s[34:35]
	s_mov_b32 m0, s81
	s_add_i32 s83, s19, 0xa000
	global_load_lds_dwordx4 v[2:3], off
	v_lshl_add_u64 v[2:3], v[12:13], 0, s[34:35]
	s_mov_b32 m0, s83
	v_bfe_u32 v161, v208, 4, 2
	global_load_lds_dwordx4 v[2:3], off
	s_add_i32 m0, s19, 0x1c000
	v_lshl_add_u64 v[2:3], v[6:7], 0, s[34:35]
	global_load_lds_dwordx4 v[2:3], off
	v_lshl_add_u64 v[2:3], v[8:9], 0, s[34:35]
	s_add_i32 m0, s19, 0x1e000
	s_add_i32 s96, s29, -2
	global_load_lds_dwordx4 v[2:3], off
	v_lshlrev_b32_e32 v2, 6, v160
	v_lshlrev_b32_e32 v3, 2, v160
	v_lshl_or_b32 v2, v161, 4, v2
	v_and_b32_e32 v3, 32, v3
	v_bitop3_b32 v4, s6, v2, v3 bitop3:0xf6
	v_bitop3_b32 v162, s38, v2, v3 bitop3:0xf6
	v_add_u32_e32 v2, v16, v14
	v_add_lshl_u32 v2, v2, v15, 1
	v_mov_b32_e32 v3, v1
	s_waitcnt vmcnt(6)
	v_lshl_add_u64 v[152:153], s[26:27], 0, v[2:3]
	v_add_u32_e32 v2, v19, v17
	s_cmpk_lt_u32 s2, 0x100
	v_add_lshl_u32 v2, v2, v18, 1
	s_cselect_b64 s[78:79], -1, 0
	s_ashr_i32 s97, s12, 31
	s_ashr_i32 s98, s28, 31
	v_lshl_add_u64 v[154:155], s[26:27], 0, v[2:3]
	s_mov_b32 s27, 0
	v_add_u32_e32 v163, 0, v4
	s_barrier
	s_mov_b32 s52, 0
	s_branch .LBB0_177
.Lzskip_gdn:
	v_mov_b64_e32 v[20:21], 0
	v_mov_b64_e32 v[22:23], 0
	v_mov_b64_e32 v[24:25], 0
	v_mov_b64_e32 v[26:27], 0
	v_mov_b64_e32 v[28:29], 0
	v_mov_b64_e32 v[30:31], 0
	v_mov_b64_e32 v[32:33], 0
	v_mov_b64_e32 v[34:35], 0
	v_mov_b64_e32 v[36:37], 0
	v_mov_b64_e32 v[38:39], 0
	v_mov_b64_e32 v[40:41], 0
	v_mov_b64_e32 v[42:43], 0
	v_mov_b64_e32 v[44:45], 0
	v_mov_b64_e32 v[46:47], 0
	s_branch .LBB0_183
	s_nop 0
	s_nop 0
	s_nop 0
	s_nop 0
	s_nop 0
	s_nop 0
	s_nop 0
	s_nop 0
	s_nop 0
	s_nop 0
	s_nop 0
	s_nop 0
	s_nop 0
	s_nop 0
	s_nop 0
	s_nop 0
	s_nop 0
	s_nop 0
	s_nop 0
	s_nop 0
	s_nop 0
	s_nop 0
	s_nop 0
	s_nop 0

.LBB0_187:
	s_add_u32 s40, s94, 0x80
	v_mov_b64_e32 v[56:57], 0
	s_addc_u32 s41, s95, 0
	v_mov_b64_e32 v[58:59], 0
	s_add_u32 s94, s92, 0x100
	v_mov_b64_e32 v[60:61], 0
	v_mov_b64_e32 v[2:3], 0
	v_mov_b64_e32 v[62:63], 0
	v_mov_b64_e32 v[64:65], 0
	v_mov_b64_e32 v[66:67], 0
	v_mov_b64_e32 v[68:69], 0
	v_mov_b64_e32 v[70:71], 0
	v_mov_b64_e32 v[72:73], 0
	v_mov_b64_e32 v[74:75], 0
	v_mov_b64_e32 v[76:77], 0
	v_mov_b64_e32 v[78:79], 0
	v_mov_b64_e32 v[80:81], 0
	v_mov_b64_e32 v[82:83], 0
	v_mov_b64_e32 v[84:85], 0
	v_mov_b64_e32 v[86:87], 0
	v_mov_b64_e32 v[88:89], 0
	v_mov_b64_e32 v[90:91], 0
	v_mov_b64_e32 v[92:93], 0
	v_mov_b64_e32 v[94:95], 0
	v_mov_b64_e32 v[96:97], 0
	v_mov_b64_e32 v[98:99], 0
	v_mov_b64_e32 v[100:101], 0
	v_mov_b64_e32 v[102:103], 0
	v_mov_b64_e32 v[104:105], 0
	v_mov_b64_e32 v[114:115], 0
	v_mov_b64_e32 v[116:117], 0
	v_mov_b64_e32 v[118:119], 0
	v_mov_b64_e32 v[120:121], 0
	v_mov_b64_e32 v[130:131], 0
	v_mov_b64_e32 v[132:133], 0
	v_mov_b64_e32 v[134:135], 0
	v_mov_b64_e32 v[136:137], 0
	v_mov_b64_e32 v[138:139], 0
	v_mov_b64_e32 v[140:141], 0
	v_mov_b64_e32 v[142:143], 0
	v_mov_b64_e32 v[144:145], 0
	s_addc_u32 s95, s93, 0
	s_mov_b32 s92, 0
	s_cmp_eq_u32 s52, 0
	s_cbranch_scc1 .Lrb_gdn
	s_mov_b32 s52, 0
	s_barrier
.Lrb_gdn:
.LBB0_188:
	s_add_i32 vcc_lo, s92, 2
	s_add_u32 s68, s40, 0x80
	s_addc_u32 s69, s41, 0
	s_add_i32 s70, 0, 0x10000
	s_cmp_eq_u32 s96, s92
	s_cselect_b32 s93, s89, s69
	s_cselect_b32 s92, s88, s68
	s_cselect_b32 s69, s91, s95
	s_cselect_b32 s68, s90, s94
	s_add_i32 s71, 0, 0x14000
	v_add_u32_e32 v126, s70, v162
	v_add_u32_e32 v172, s71, v162
	ds_read_b128 v[106:109], v126
	ds_read_b128 v[110:113], v126 offset:1024
	ds_read_b128 v[122:125], v126 offset:2048
	ds_read_b128 v[126:129], v126 offset:3072
	ds_read_b128 v[156:159], v172
	ds_read_b128 v[164:167], v172 offset:1024
	ds_read_b128 v[168:171], v172 offset:2048
	ds_read_b128 v[172:175], v172 offset:3072
	v_lshl_add_u64 v[210:211], s[40:41], 0, v[152:153]
	s_add_i32 m0, s19, 0xc000
	ds_read_b128 v[176:179], v163
	ds_read_b128 v[180:183], v163 offset:1024
	ds_read_b128 v[184:187], v163 offset:2048
	ds_read_b128 v[188:191], v163 offset:3072
	ds_read_b128 v[192:195], v163 offset:4096
	ds_read_b128 v[196:199], v163 offset:5120
	ds_read_b128 v[200:203], v163 offset:6144
	ds_read_b128 v[204:207], v163 offset:7168
	global_load_lds_dwordx4 v[210:211], off
	v_lshl_add_u64 v[210:211], s[40:41], 0, v[154:155]
	s_add_i32 m0, s19, 0xe000
	s_nop 0
	global_load_lds_dwordx4 v[210:211], off
	s_waitcnt vmcnt(8)
	s_waitcnt lgkmcnt(0)
	s_barrier
	s_waitcnt lgkmcnt(0)
	v_mfma_f32_16x16x32_bf16 v[142:145], v[106:109], v[176:179], v[142:145]
	v_mfma_f32_16x16x32_bf16 v[138:141], v[122:125], v[176:179], v[138:141]
	v_mfma_f32_16x16x32_bf16 v[118:121], v[106:109], v[184:187], v[118:121]
	v_mfma_f32_16x16x32_bf16 v[114:117], v[122:125], v[184:187], v[114:117]
	v_mfma_f32_16x16x32_bf16 v[94:97], v[106:109], v[192:195], v[94:97]
	v_mfma_f32_16x16x32_bf16 v[90:93], v[122:125], v[192:195], v[90:93]
	v_mfma_f32_16x16x32_bf16 v[78:81], v[106:109], v[200:203], v[78:81]
	v_mfma_f32_16x16x32_bf16 v[74:77], v[122:125], v[200:203], v[74:77]
	v_mfma_f32_16x16x32_bf16 v[134:137], v[156:159], v[176:179], v[134:137]
	v_mfma_f32_16x16x32_bf16 v[130:133], v[168:171], v[176:179], v[130:133]
	v_mfma_f32_16x16x32_bf16 v[102:105], v[156:159], v[184:187], v[102:105]
	v_mfma_f32_16x16x32_bf16 v[98:101], v[168:171], v[184:187], v[98:101]
	v_mfma_f32_16x16x32_bf16 v[86:89], v[156:159], v[192:195], v[86:89]
	v_mfma_f32_16x16x32_bf16 v[82:85], v[168:171], v[192:195], v[82:85]
	v_mfma_f32_16x16x32_bf16 v[70:73], v[156:159], v[200:203], v[70:73]
	v_mfma_f32_16x16x32_bf16 v[66:69], v[168:171], v[200:203], v[66:69]
	v_mfma_f32_16x16x32_bf16 v[142:145], v[110:113], v[180:183], v[142:145]
	v_mfma_f32_16x16x32_bf16 v[138:141], v[126:129], v[180:183], v[138:141]
	v_mfma_f32_16x16x32_bf16 v[118:121], v[110:113], v[188:191], v[118:121]
	v_mfma_f32_16x16x32_bf16 v[114:117], v[126:129], v[188:191], v[114:117]
	v_mfma_f32_16x16x32_bf16 v[94:97], v[110:113], v[196:199], v[94:97]
	v_mfma_f32_16x16x32_bf16 v[90:93], v[126:129], v[196:199], v[90:93]
	v_mfma_f32_16x16x32_bf16 v[78:81], v[110:113], v[204:207], v[78:81]
	v_mfma_f32_16x16x32_bf16 v[74:77], v[126:129], v[204:207], v[74:77]
	v_mfma_f32_16x16x32_bf16 v[134:137], v[164:167], v[180:183], v[134:137]
	v_mfma_f32_16x16x32_bf16 v[130:133], v[172:175], v[180:183], v[130:133]
	v_mfma_f32_16x16x32_bf16 v[102:105], v[164:167], v[188:191], v[102:105]
	v_mfma_f32_16x16x32_bf16 v[98:101], v[172:175], v[188:191], v[98:101]
	v_mfma_f32_16x16x32_bf16 v[86:89], v[164:167], v[196:199], v[86:89]
	v_mfma_f32_16x16x32_bf16 v[82:85], v[172:175], v[196:199], v[82:85]
	v_mfma_f32_16x16x32_bf16 v[70:73], v[164:167], v[204:207], v[70:73]
	v_mfma_f32_16x16x32_bf16 v[66:69], v[172:175], v[204:207], v[66:69]
	s_barrier
	s_add_i32 s70, s70, s18
	v_lshl_add_u64 v[210:211], s[68:69], 0, v[0:1]
	s_mov_b32 m0, s70
	ds_read_b128 v[176:179], v163 offset:16384
	ds_read_b128 v[180:183], v163 offset:17408
	ds_read_b128 v[184:187], v163 offset:18432
	ds_read_b128 v[188:191], v163 offset:19456
	ds_read_b128 v[192:195], v163 offset:20480
	ds_read_b128 v[196:199], v163 offset:21504
	ds_read_b128 v[200:203], v163 offset:22528
	ds_read_b128 v[204:207], v163 offset:23552
	global_load_lds_dwordx4 v[210:211], off
	s_add_i32 m0, s70, 0x2000
	v_lshl_add_u64 v[212:213], s[68:69], 0, v[150:151]
	s_add_u32 s68, s68, s26
	s_addc_u32 s69, s69, 0
	s_add_i32 s70, s71, s18
	global_load_lds_dwordx4 v[212:213], off
	v_lshl_add_u64 v[214:215], s[68:69], 0, v[0:1]
	s_mov_b32 m0, s70
	v_lshl_add_u64 v[216:217], s[68:69], 0, v[150:151]
	global_load_lds_dwordx4 v[214:215], off
	s_add_i32 m0, s70, 0x2000
	v_lshl_add_u64 v[218:219], s[92:93], 0, v[146:147]
	global_load_lds_dwordx4 v[216:217], off
	s_mov_b32 m0, s19
	v_lshl_add_u64 v[220:221], s[92:93], 0, v[148:149]
	global_load_lds_dwordx4 v[218:219], off
	s_mov_b32 m0, s20
	s_nop 0
	global_load_lds_dwordx4 v[220:221], off
	s_waitcnt vmcnt(8)
	s_waitcnt lgkmcnt(0)
	s_barrier
	s_waitcnt lgkmcnt(0)
	v_mfma_f32_16x16x32_bf16 v[62:65], v[106:109], v[176:179], v[62:65]
	v_mfma_f32_16x16x32_bf16 v[58:61], v[122:125], v[176:179], v[58:61]
	v_mfma_f32_16x16x32_bf16 v[46:49], v[106:109], v[184:187], v[46:49]
	v_mfma_f32_16x16x32_bf16 v[42:45], v[122:125], v[184:187], v[42:45]
	v_mfma_f32_16x16x32_bf16 v[30:33], v[106:109], v[192:195], v[30:33]
	v_mfma_f32_16x16x32_bf16 v[26:29], v[122:125], v[192:195], v[26:29]
	v_mfma_f32_16x16x32_bf16 v[14:17], v[106:109], v[200:203], v[14:17]
	v_mfma_f32_16x16x32_bf16 v[10:13], v[122:125], v[200:203], v[10:13]
	v_mfma_f32_16x16x32_bf16 v[54:57], v[156:159], v[176:179], v[54:57]
	v_mfma_f32_16x16x32_bf16 v[50:53], v[168:171], v[176:179], v[50:53]
	v_mfma_f32_16x16x32_bf16 v[38:41], v[156:159], v[184:187], v[38:41]
	v_mfma_f32_16x16x32_bf16 v[34:37], v[168:171], v[184:187], v[34:37]
	v_mfma_f32_16x16x32_bf16 v[22:25], v[156:159], v[192:195], v[22:25]
	v_mfma_f32_16x16x32_bf16 v[18:21], v[168:171], v[192:195], v[18:21]
	v_mfma_f32_16x16x32_bf16 v[6:9], v[156:159], v[200:203], v[6:9]
	v_mfma_f32_16x16x32_bf16 v[2:5], v[168:171], v[200:203], v[2:5]
	v_mfma_f32_16x16x32_bf16 v[62:65], v[110:113], v[180:183], v[62:65]
	v_mfma_f32_16x16x32_bf16 v[58:61], v[126:129], v[180:183], v[58:61]
	v_mfma_f32_16x16x32_bf16 v[46:49], v[110:113], v[188:191], v[46:49]
	v_mfma_f32_16x16x32_bf16 v[42:45], v[126:129], v[188:191], v[42:45]
	v_mfma_f32_16x16x32_bf16 v[30:33], v[110:113], v[196:199], v[30:33]
	v_mfma_f32_16x16x32_bf16 v[26:29], v[126:129], v[196:199], v[26:29]
	v_mfma_f32_16x16x32_bf16 v[14:17], v[110:113], v[204:207], v[14:17]
	v_mfma_f32_16x16x32_bf16 v[10:13], v[126:129], v[204:207], v[10:13]
	v_mfma_f32_16x16x32_bf16 v[54:57], v[164:167], v[180:183], v[54:57]
	v_mfma_f32_16x16x32_bf16 v[50:53], v[172:175], v[180:183], v[50:53]
	v_mfma_f32_16x16x32_bf16 v[38:41], v[164:167], v[188:191], v[38:41]
	v_mfma_f32_16x16x32_bf16 v[34:37], v[172:175], v[188:191], v[34:37]
	v_mfma_f32_16x16x32_bf16 v[22:25], v[164:167], v[196:199], v[22:25]
	v_mfma_f32_16x16x32_bf16 v[18:21], v[172:175], v[196:199], v[18:21]
	v_mfma_f32_16x16x32_bf16 v[6:9], v[164:167], v[204:207], v[6:9]
	v_mfma_f32_16x16x32_bf16 v[2:5], v[172:175], v[204:207], v[2:5]
	s_barrier
	s_add_i32 s70, 0, 0x18000
	s_add_i32 s71, 0, 0x1c000
	v_add_u32_e32 v126, s70, v162
	v_add_u32_e32 v172, s71, v162
	ds_read_b128 v[106:109], v126
	ds_read_b128 v[110:113], v126 offset:1024
	ds_read_b128 v[122:125], v126 offset:2048
	ds_read_b128 v[126:129], v126 offset:3072
	ds_read_b128 v[156:159], v172
	ds_read_b128 v[164:167], v172 offset:1024
	ds_read_b128 v[168:171], v172 offset:2048
	ds_read_b128 v[172:175], v172 offset:3072
	s_add_u32 s68, s92, s26
	s_addc_u32 s69, s93, 0
	s_mov_b32 m0, s21
	v_lshl_add_u64 v[222:223], s[68:69], 0, v[146:147]
	ds_read_b128 v[176:179], v163 offset:32768
	ds_read_b128 v[180:183], v163 offset:33792
	ds_read_b128 v[184:187], v163 offset:34816
	ds_read_b128 v[188:191], v163 offset:35840
	ds_read_b128 v[192:195], v163 offset:36864
	ds_read_b128 v[196:199], v163 offset:37888
	ds_read_b128 v[200:203], v163 offset:38912
	ds_read_b128 v[204:207], v163 offset:39936
	global_load_lds_dwordx4 v[222:223], off
	v_lshl_add_u64 v[222:223], s[68:69], 0, v[148:149]
	s_mov_b32 m0, s22
	s_nop 0
	global_load_lds_dwordx4 v[222:223], off
	s_waitcnt vmcnt(8)
	s_waitcnt lgkmcnt(0)
	s_barrier
	s_waitcnt lgkmcnt(0)
	v_mfma_f32_16x16x32_bf16 v[142:145], v[106:109], v[176:179], v[142:145]
	v_mfma_f32_16x16x32_bf16 v[138:141], v[122:125], v[176:179], v[138:141]
	v_mfma_f32_16x16x32_bf16 v[118:121], v[106:109], v[184:187], v[118:121]
	v_mfma_f32_16x16x32_bf16 v[114:117], v[122:125], v[184:187], v[114:117]
	v_mfma_f32_16x16x32_bf16 v[94:97], v[106:109], v[192:195], v[94:97]
	v_mfma_f32_16x16x32_bf16 v[90:93], v[122:125], v[192:195], v[90:93]
	v_mfma_f32_16x16x32_bf16 v[78:81], v[106:109], v[200:203], v[78:81]
	v_mfma_f32_16x16x32_bf16 v[74:77], v[122:125], v[200:203], v[74:77]
	v_mfma_f32_16x16x32_bf16 v[134:137], v[156:159], v[176:179], v[134:137]
	v_mfma_f32_16x16x32_bf16 v[130:133], v[168:171], v[176:179], v[130:133]
	v_mfma_f32_16x16x32_bf16 v[102:105], v[156:159], v[184:187], v[102:105]
	v_mfma_f32_16x16x32_bf16 v[98:101], v[168:171], v[184:187], v[98:101]
	v_mfma_f32_16x16x32_bf16 v[86:89], v[156:159], v[192:195], v[86:89]
	v_mfma_f32_16x16x32_bf16 v[82:85], v[168:171], v[192:195], v[82:85]
	v_mfma_f32_16x16x32_bf16 v[70:73], v[156:159], v[200:203], v[70:73]
	v_mfma_f32_16x16x32_bf16 v[66:69], v[168:171], v[200:203], v[66:69]
	v_mfma_f32_16x16x32_bf16 v[142:145], v[110:113], v[180:183], v[142:145]
	v_mfma_f32_16x16x32_bf16 v[138:141], v[126:129], v[180:183], v[138:141]
	v_mfma_f32_16x16x32_bf16 v[118:121], v[110:113], v[188:191], v[118:121]
	v_mfma_f32_16x16x32_bf16 v[114:117], v[126:129], v[188:191], v[114:117]
	v_mfma_f32_16x16x32_bf16 v[94:97], v[110:113], v[196:199], v[94:97]
	v_mfma_f32_16x16x32_bf16 v[90:93], v[126:129], v[196:199], v[90:93]
	v_mfma_f32_16x16x32_bf16 v[78:81], v[110:113], v[204:207], v[78:81]
	v_mfma_f32_16x16x32_bf16 v[74:77], v[126:129], v[204:207], v[74:77]
	v_mfma_f32_16x16x32_bf16 v[134:137], v[164:167], v[180:183], v[134:137]
	v_mfma_f32_16x16x32_bf16 v[130:133], v[172:175], v[180:183], v[130:133]
	v_mfma_f32_16x16x32_bf16 v[102:105], v[164:167], v[188:191], v[102:105]
	v_mfma_f32_16x16x32_bf16 v[98:101], v[172:175], v[188:191], v[98:101]
	v_mfma_f32_16x16x32_bf16 v[86:89], v[164:167], v[196:199], v[86:89]
	v_mfma_f32_16x16x32_bf16 v[82:85], v[172:175], v[196:199], v[82:85]
	v_mfma_f32_16x16x32_bf16 v[70:73], v[164:167], v[204:207], v[70:73]
	v_mfma_f32_16x16x32_bf16 v[66:69], v[172:175], v[204:207], v[66:69]
	s_barrier
	s_add_i32 s68, s70, s18
	v_lshl_add_u64 v[210:211], v[210:211], 0, s[34:35]
	s_mov_b32 m0, s68
	ds_read_b128 v[176:179], v163 offset:49152
	ds_read_b128 v[180:183], v163 offset:50176
	ds_read_b128 v[184:187], v163 offset:51200
	ds_read_b128 v[188:191], v163 offset:52224
	ds_read_b128 v[192:195], v163 offset:53248
	ds_read_b128 v[196:199], v163 offset:54272
	ds_read_b128 v[200:203], v163 offset:55296
	ds_read_b128 v[204:207], v163 offset:56320
	global_load_lds_dwordx4 v[210:211], off
	v_lshl_add_u64 v[210:211], v[212:213], 0, s[34:35]
	s_add_i32 m0, s68, 0x2000
	s_add_i32 s68, s71, s18
	global_load_lds_dwordx4 v[210:211], off
	v_lshl_add_u64 v[210:211], v[214:215], 0, s[34:35]
	s_mov_b32 m0, s68
	s_nop 0
	global_load_lds_dwordx4 v[210:211], off
	v_lshl_add_u64 v[210:211], v[216:217], 0, s[34:35]
	s_add_i32 m0, s68, 0x2000
	s_nop 0
	global_load_lds_dwordx4 v[210:211], off
	v_lshl_add_u64 v[210:211], v[218:219], 0, s[34:35]
	s_mov_b32 m0, s81
	s_nop 0
	global_load_lds_dwordx4 v[210:211], off
	v_lshl_add_u64 v[210:211], v[220:221], 0, s[34:35]
	s_mov_b32 m0, s83
	s_nop 0
	global_load_lds_dwordx4 v[210:211], off
	s_waitcnt vmcnt(8)
	s_waitcnt lgkmcnt(0)
	s_barrier
	s_waitcnt lgkmcnt(0)
	v_mfma_f32_16x16x32_bf16 v[62:65], v[106:109], v[176:179], v[62:65]
	v_mfma_f32_16x16x32_bf16 v[58:61], v[122:125], v[176:179], v[58:61]
	v_mfma_f32_16x16x32_bf16 v[46:49], v[106:109], v[184:187], v[46:49]
	v_mfma_f32_16x16x32_bf16 v[42:45], v[122:125], v[184:187], v[42:45]
	v_mfma_f32_16x16x32_bf16 v[30:33], v[106:109], v[192:195], v[30:33]
	v_mfma_f32_16x16x32_bf16 v[26:29], v[122:125], v[192:195], v[26:29]
	v_mfma_f32_16x16x32_bf16 v[14:17], v[106:109], v[200:203], v[14:17]
	v_mfma_f32_16x16x32_bf16 v[10:13], v[122:125], v[200:203], v[10:13]
	v_mfma_f32_16x16x32_bf16 v[54:57], v[156:159], v[176:179], v[54:57]
	v_mfma_f32_16x16x32_bf16 v[50:53], v[168:171], v[176:179], v[50:53]
	v_mfma_f32_16x16x32_bf16 v[38:41], v[156:159], v[184:187], v[38:41]
	v_mfma_f32_16x16x32_bf16 v[34:37], v[168:171], v[184:187], v[34:37]
	v_mfma_f32_16x16x32_bf16 v[22:25], v[156:159], v[192:195], v[22:25]
	v_mfma_f32_16x16x32_bf16 v[18:21], v[168:171], v[192:195], v[18:21]
	v_mfma_f32_16x16x32_bf16 v[6:9], v[156:159], v[200:203], v[6:9]
	v_mfma_f32_16x16x32_bf16 v[2:5], v[168:171], v[200:203], v[2:5]
	v_mfma_f32_16x16x32_bf16 v[62:65], v[110:113], v[180:183], v[62:65]
	v_mfma_f32_16x16x32_bf16 v[58:61], v[126:129], v[180:183], v[58:61]
	v_mfma_f32_16x16x32_bf16 v[46:49], v[110:113], v[188:191], v[46:49]
	v_mfma_f32_16x16x32_bf16 v[42:45], v[126:129], v[188:191], v[42:45]
	v_mfma_f32_16x16x32_bf16 v[30:33], v[110:113], v[196:199], v[30:33]
	v_mfma_f32_16x16x32_bf16 v[26:29], v[126:129], v[196:199], v[26:29]
	v_mfma_f32_16x16x32_bf16 v[14:17], v[110:113], v[204:207], v[14:17]
	v_mfma_f32_16x16x32_bf16 v[10:13], v[126:129], v[204:207], v[10:13]
	v_mfma_f32_16x16x32_bf16 v[54:57], v[164:167], v[180:183], v[54:57]
	v_mfma_f32_16x16x32_bf16 v[50:53], v[172:175], v[180:183], v[50:53]
	v_mfma_f32_16x16x32_bf16 v[38:41], v[164:167], v[188:191], v[38:41]
	v_mfma_f32_16x16x32_bf16 v[34:37], v[172:175], v[188:191], v[34:37]
	v_mfma_f32_16x16x32_bf16 v[22:25], v[164:167], v[196:199], v[22:25]
	v_mfma_f32_16x16x32_bf16 v[18:21], v[172:175], v[196:199], v[18:21]
	v_mfma_f32_16x16x32_bf16 v[6:9], v[164:167], v[204:207], v[6:9]
	v_mfma_f32_16x16x32_bf16 v[2:5], v[172:175], v[204:207], v[2:5]
	s_barrier
	s_add_u32 s40, s40, 0x100
	s_addc_u32 s41, s41, 0
	s_add_u32 s94, s94, 0x100
	s_addc_u32 s95, s95, 0
	s_cmp_ge_u32 vcc_lo, s29
	s_mov_b32 s92, vcc_lo
	s_cbranch_scc0 .LBB0_188
	s_and_b64 vcc, exec, s[78:79]
	s_cbranch_vccz .LBB0_191
	s_barrier

.LBB0_207:
	s_or_b64 exec, exec, s[40:41]
	s_and_b64 vcc, exec, s[38:39]
	s_mov_b64 s[38:39], -1
	s_cbranch_vccnz .LBB0_176
	s_andn2_b64 vcc, exec, s[74:75]
	s_cbranch_vccnz .LBB0_175
	s_mov_b32 s52, 1
	s_branch .LBB0_175

.LBB0_237:
	s_add_u32 s68, s24, 0x19b69c00
	s_addc_u32 s69, s25, 0
	s_and_b32 s18, s6, 3
	s_add_i32 m0, s81, 0x18000
	v_lshl_add_u64 v[8:9], v[8:9], 0, s[34:35]
	s_lshl_b32 s6, s15, 13
	s_lshl_b32 s21, s18, 12
	s_waitcnt vmcnt(2)
	s_barrier
	global_load_lds_dwordx4 v[8:9], off
	v_lshl_add_u64 v[6:7], v[6:7], 0, s[34:35]
	s_add_i32 m0, s81, 0x1a000
	s_add_i32 s19, s81, 0x8000
	s_add_i32 s20, s81, 0xa000
	global_load_lds_dwordx4 v[6:7], off
	v_lshl_add_u64 v[2:3], v[2:3], 0, s[34:35]
	s_mov_b32 m0, s19
	s_add_u32 s22, s92, 0x40080
	global_load_lds_dwordx4 v[2:3], off
	v_lshl_add_u64 v[2:3], v[4:5], 0, s[34:35]
	s_mov_b32 m0, s20
	s_addc_u32 s23, s93, 0
	global_load_lds_dwordx4 v[2:3], off
	s_add_i32 m0, s81, 0x1c000
	v_lshl_add_u64 v[2:3], s[22:23], 0, v[164:165]
	global_load_lds_dwordx4 v[2:3], off
	v_lshl_add_u64 v[2:3], s[22:23], 0, v[168:169]
	s_add_i32 m0, s81, 0x1e000
	v_bfe_u32 v179, v208, 4, 2
	global_load_lds_dwordx4 v[2:3], off
	v_lshlrev_b32_e32 v2, 6, v177
	v_lshlrev_b32_e32 v3, 2, v177
	v_lshl_or_b32 v2, v179, 4, v2
	v_and_b32_e32 v3, 32, v3
	v_bitop3_b32 v4, s6, v2, v3 bitop3:0xf6
	v_bitop3_b32 v181, s21, v2, v3 bitop3:0xf6
	v_lshlrev_b32_e32 v2, 14, v0
	v_and_b32_e32 v2, 0xffff8000, v2
	v_lshl_add_u32 v2, v10, 11, v2
	v_and_b32_e32 v0, 1, v0
	s_cmpk_lt_u32 s2, 0x100
	v_lshl_or_b32 v0, v0, 6, v2
	s_cselect_b64 s[74:75], -1, 0
	s_ashr_i32 s21, s12, 31
	s_ashr_i32 s22, s28, 31
	v_lshl_add_u32 v170, v11, 1, v0
	v_lshlrev_b32_e32 v0, 14, v12
	s_add_u32 s78, s44, 0x2c00
	v_and_b32_e32 v0, 0xffff8000, v0
	s_waitcnt vmcnt(6)
	s_addc_u32 s79, s45, 0
	v_lshl_add_u32 v0, v13, 11, v0
	v_and_b32_e32 v2, 1, v12
	s_add_u32 s26, s44, 0x5800
	v_lshl_or_b32 v0, v2, 6, v0
	s_addc_u32 s27, s45, 0
	v_mov_b32_e32 v171, v1
	v_lshl_add_u32 v172, v14, 1, v0
	v_mov_b32_e32 v173, v1
	s_mov_b32 s23, 0
	v_add_u32_e32 v189, 0, v4
	s_barrier
	s_mov_b32 s52, 0
	s_branch .LBB0_240
.Lzskip_gup:
	v_mov_b64_e32 v[30:31], 0
	v_mov_b64_e32 v[32:33], 0
	v_mov_b64_e32 v[34:35], 0
	v_mov_b64_e32 v[36:37], 0
	v_mov_b64_e32 v[38:39], 0
	v_mov_b64_e32 v[40:41], 0
	v_mov_b64_e32 v[42:43], 0
	v_mov_b64_e32 v[44:45], 0
	v_mov_b64_e32 v[46:47], 0
	v_mov_b64_e32 v[48:49], 0
	v_mov_b64_e32 v[50:51], 0
	v_mov_b64_e32 v[52:53], 0
	v_mov_b64_e32 v[54:55], 0
	v_mov_b64_e32 v[56:57], 0
	v_mov_b64_e32 v[58:59], 0
	v_mov_b64_e32 v[60:61], 0
	v_mov_b64_e32 v[62:63], 0
	v_mov_b64_e32 v[64:65], 0
	v_mov_b64_e32 v[66:67], 0
	v_mov_b64_e32 v[68:69], 0
	v_mov_b64_e32 v[70:71], 0
	v_mov_b64_e32 v[72:73], 0
	v_mov_b64_e32 v[86:87], 0
	s_branch .LBB0_242
	s_nop 0
	s_nop 0
	s_nop 0
	s_nop 0
	s_nop 0
	s_nop 0
	s_nop 0
	s_nop 0
	s_nop 0
	s_nop 0
	s_nop 0
	s_nop 0
	s_nop 0
	s_nop 0
	s_nop 0
	s_nop 0
	s_nop 0
	s_nop 0
	s_nop 0
	s_nop 0
	s_nop 0
	s_nop 0
	s_nop 0
	s_nop 0
	s_nop 0
	s_nop 0
	s_nop 0
	s_nop 0
	s_nop 0
	s_nop 0
	s_nop 0

.LBB0_242:
	s_ashr_i32 s95, s94, 31
	v_mov_b64_e32 v[88:89], 0
	s_lshl_b64 s[70:71], s[94:95], 19
	v_mov_b64_e32 v[90:91], 0
	s_add_u32 s90, s36, s70
	v_mov_b64_e32 v[92:93], 0
	s_addc_u32 s91, s37, s71
	v_mov_b64_e32 v[94:95], 0
	s_and_b64 s[70:71], s[38:39], exec
	v_mov_b64_e32 v[96:97], 0
	s_cselect_b32 s2, s91, s43
	v_mov_b64_e32 v[98:99], 0
	s_cselect_b32 s6, s90, s42
	v_mov_b64_e32 v[100:101], 0
	s_ashr_i32 s89, s88, 31
	v_mov_b64_e32 v[102:103], 0
	s_lshl_b64 s[70:71], s[88:89], 19
	v_mov_b64_e32 v[104:105], 0
	s_add_u32 s96, s50, s70
	v_mov_b64_e32 v[106:107], 0
	s_addc_u32 s97, s51, s71
	v_mov_b64_e32 v[108:109], 0
	s_and_b64 s[70:71], s[38:39], exec
	v_mov_b64_e32 v[110:111], 0
	s_cselect_b32 s41, s97, s93
	v_mov_b64_e32 v[112:113], 0
	s_cselect_b32 s48, s96, s92
	v_mov_b64_e32 v[114:115], 0
	s_add_u32 s42, s42, 0x40080
	v_mov_b64_e32 v[116:117], 0
	s_addc_u32 s43, s43, 0
	v_mov_b64_e32 v[118:119], 0
	s_add_u32 s77, s92, 0x100
	v_mov_b64_e32 v[120:121], 0
	v_mov_b64_e32 v[2:3], 0
	v_mov_b64_e32 v[122:123], 0
	v_mov_b64_e32 v[124:125], 0
	v_mov_b64_e32 v[126:127], 0
	v_mov_b64_e32 v[128:129], 0
	v_mov_b64_e32 v[130:131], 0
	v_mov_b64_e32 v[132:133], 0
	v_mov_b64_e32 v[134:135], 0
	v_mov_b64_e32 v[136:137], 0
	v_mov_b64_e32 v[138:139], 0
	v_mov_b64_e32 v[140:141], 0
	v_mov_b64_e32 v[142:143], 0
	v_mov_b64_e32 v[144:145], 0
	v_mov_b64_e32 v[146:147], 0
	v_mov_b64_e32 v[148:149], 0
	v_mov_b64_e32 v[150:151], 0
	v_mov_b64_e32 v[152:153], 0
	s_addc_u32 s89, s93, 0
	s_mov_b32 s95, -2
	s_waitcnt lgkmcnt(0)
	s_cmp_eq_u32 s52, 0
	s_cbranch_scc1 .Lrb_gup
	s_mov_b32 s52, 0
	s_barrier
.Lrb_gup:
.LBB0_243:
	s_add_u32 s70, s42, 0xfffc0080
	s_addc_u32 s71, s43, -1
	s_add_i32 s72, 0, 0x10000
	s_cmp_eq_u32 s95, 12
	s_cselect_b32 vcc_hi, s2, s71
	s_cselect_b32 vcc_lo, s6, s70
	v_add_u32_e32 v0, s72, v181
	s_cselect_b32 s93, s41, s89
	s_cselect_b32 s92, s48, s77
	s_add_i32 s73, 0, 0x14000
	ds_read_b128 v[14:17], v0
	ds_read_b128 v[22:25], v0 offset:1024
	ds_read_b128 v[26:29], v0 offset:2048
	ds_read_b128 v[74:77], v0 offset:3072
	v_add_u32_e32 v0, s73, v181
	ds_read_b128 v[78:81], v0
	ds_read_b128 v[82:85], v0 offset:1024
	ds_read_b128 v[154:157], v0 offset:2048
	ds_read_b128 v[158:161], v0 offset:3072
	v_lshl_add_u64 v[174:175], s[42:43], 0, v[170:171]
	s_add_i32 m0, s81, 0xc000
	ds_read_b128 v[182:185], v189
	ds_read_b128 v[190:193], v189 offset:1024
	ds_read_b128 v[194:197], v189 offset:2048
	ds_read_b128 v[198:201], v189 offset:3072
	ds_read_b128 v[202:205], v189 offset:4096
	ds_read_b128 v[210:213], v189 offset:5120
	ds_read_b128 v[214:217], v189 offset:6144
	ds_read_b128 v[218:221], v189 offset:7168
	global_load_lds_dwordx4 v[174:175], off
	v_lshl_add_u64 v[174:175], s[42:43], 0, v[172:173]
	s_add_i32 m0, s81, 0xe000
	s_nop 0
	global_load_lds_dwordx4 v[174:175], off
	s_waitcnt vmcnt(8)
	s_waitcnt lgkmcnt(0)
	s_barrier
	s_waitcnt lgkmcnt(0)
	v_mfma_f32_16x16x32_bf16 v[150:153], v[14:17], v[182:185], v[150:153]
	v_mfma_f32_16x16x32_bf16 v[58:61], v[26:29], v[182:185], v[58:61]
	v_mfma_f32_16x16x32_bf16 v[126:129], v[14:17], v[194:197], v[126:129]
	v_mfma_f32_16x16x32_bf16 v[122:125], v[26:29], v[194:197], v[122:125]
	v_mfma_f32_16x16x32_bf16 v[118:121], v[14:17], v[202:205], v[118:121]
	v_mfma_f32_16x16x32_bf16 v[114:117], v[26:29], v[202:205], v[114:117]
	v_mfma_f32_16x16x32_bf16 v[134:137], v[14:17], v[214:217], v[134:137]
	v_mfma_f32_16x16x32_bf16 v[130:133], v[26:29], v[214:217], v[130:133]
	v_mfma_f32_16x16x32_bf16 v[142:145], v[78:81], v[182:185], v[142:145]
	v_mfma_f32_16x16x32_bf16 v[138:141], v[154:157], v[182:185], v[138:141]
	v_mfma_f32_16x16x32_bf16 v[110:113], v[78:81], v[194:197], v[110:113]
	v_mfma_f32_16x16x32_bf16 v[106:109], v[154:157], v[194:197], v[106:109]
	v_mfma_f32_16x16x32_bf16 v[102:105], v[78:81], v[202:205], v[102:105]
	v_mfma_f32_16x16x32_bf16 v[98:101], v[154:157], v[202:205], v[98:101]
	v_mfma_f32_16x16x32_bf16 v[94:97], v[78:81], v[214:217], v[94:97]
	v_mfma_f32_16x16x32_bf16 v[90:93], v[154:157], v[214:217], v[90:93]
	v_mfma_f32_16x16x32_bf16 v[150:153], v[22:25], v[190:193], v[150:153]
	v_mfma_f32_16x16x32_bf16 v[58:61], v[74:77], v[190:193], v[58:61]
	v_mfma_f32_16x16x32_bf16 v[126:129], v[22:25], v[198:201], v[126:129]
	v_mfma_f32_16x16x32_bf16 v[122:125], v[74:77], v[198:201], v[122:125]
	v_mfma_f32_16x16x32_bf16 v[118:121], v[22:25], v[210:213], v[118:121]
	v_mfma_f32_16x16x32_bf16 v[114:117], v[74:77], v[210:213], v[114:117]
	v_mfma_f32_16x16x32_bf16 v[134:137], v[22:25], v[218:221], v[134:137]
	v_mfma_f32_16x16x32_bf16 v[130:133], v[74:77], v[218:221], v[130:133]
	v_mfma_f32_16x16x32_bf16 v[142:145], v[82:85], v[190:193], v[142:145]
	v_mfma_f32_16x16x32_bf16 v[138:141], v[158:161], v[190:193], v[138:141]
	v_mfma_f32_16x16x32_bf16 v[110:113], v[82:85], v[198:201], v[110:113]
	v_mfma_f32_16x16x32_bf16 v[106:109], v[158:161], v[198:201], v[106:109]
	v_mfma_f32_16x16x32_bf16 v[102:105], v[82:85], v[210:213], v[102:105]
	v_mfma_f32_16x16x32_bf16 v[98:101], v[158:161], v[210:213], v[98:101]
	v_mfma_f32_16x16x32_bf16 v[94:97], v[82:85], v[218:221], v[94:97]
	v_mfma_f32_16x16x32_bf16 v[90:93], v[158:161], v[218:221], v[90:93]
	s_barrier
	s_add_i32 s70, s72, s29
	v_lshl_add_u64 v[174:175], s[92:93], 0, v[164:165]
	s_mov_b32 m0, s70
	ds_read_b128 v[182:185], v189 offset:16384
	ds_read_b128 v[190:193], v189 offset:17408
	ds_read_b128 v[194:197], v189 offset:18432
	ds_read_b128 v[198:201], v189 offset:19456
	ds_read_b128 v[202:205], v189 offset:20480
	ds_read_b128 v[210:213], v189 offset:21504
	ds_read_b128 v[214:217], v189 offset:22528
	ds_read_b128 v[218:221], v189 offset:23552
	global_load_lds_dwordx4 v[174:175], off
	s_add_i32 m0, s70, 0x2000
	s_add_u32 s70, s92, 0x40000
	v_lshl_add_u64 v[186:187], s[92:93], 0, v[168:169]
	s_addc_u32 s71, s93, 0
	s_add_i32 s72, s73, s29
	global_load_lds_dwordx4 v[186:187], off
	v_lshl_add_u64 v[206:207], s[70:71], 0, v[164:165]
	s_mov_b32 m0, s72
	v_lshl_add_u64 v[226:227], vcc, 0, v[166:167]
	global_load_lds_dwordx4 v[206:207], off
	v_lshl_add_u64 v[206:207], s[70:71], 0, v[168:169]
	s_add_i32 m0, s72, 0x2000
	s_nop 0
	global_load_lds_dwordx4 v[206:207], off
	v_lshl_add_u64 v[206:207], vcc, 0, v[162:163]
	s_mov_b32 m0, s81
	s_nop 0
	global_load_lds_dwordx4 v[206:207], off
	s_mov_b32 m0, s83
	s_nop 0
	global_load_lds_dwordx4 v[226:227], off
	s_waitcnt vmcnt(8)
	s_waitcnt lgkmcnt(0)
	s_barrier
	s_waitcnt lgkmcnt(0)
	v_mfma_f32_16x16x32_bf16 v[70:73], v[14:17], v[182:185], v[70:73]
	v_mfma_f32_16x16x32_bf16 v[66:69], v[26:29], v[182:185], v[66:69]
	v_mfma_f32_16x16x32_bf16 v[62:65], v[14:17], v[194:197], v[62:65]
	v_mfma_f32_16x16x32_bf16 v[54:57], v[26:29], v[194:197], v[54:57]
	v_mfma_f32_16x16x32_bf16 v[42:45], v[14:17], v[202:205], v[42:45]
	v_mfma_f32_16x16x32_bf16 v[38:41], v[26:29], v[202:205], v[38:41]
	v_mfma_f32_16x16x32_bf16 v[14:17], v[14:17], v[214:217], v[86:89]
	v_mfma_f32_16x16x32_bf16 v[46:49], v[154:157], v[182:185], v[46:49]
	v_mfma_f32_16x16x32_bf16 v[34:37], v[78:81], v[194:197], v[34:37]
	v_mfma_f32_16x16x32_bf16 v[30:33], v[154:157], v[194:197], v[30:33]
	v_mfma_f32_16x16x32_bf16 v[18:21], v[78:81], v[202:205], v[18:21]
	v_mfma_f32_16x16x32_bf16 v[10:13], v[154:157], v[202:205], v[10:13]
	v_mfma_f32_16x16x32_bf16 v[6:9], v[78:81], v[214:217], v[6:9]
	v_mfma_f32_16x16x32_bf16 v[2:5], v[154:157], v[214:217], v[2:5]
	v_mfma_f32_16x16x32_bf16 v[70:73], v[22:25], v[190:193], v[70:73]
	v_mfma_f32_16x16x32_bf16 v[66:69], v[74:77], v[190:193], v[66:69]
	v_mfma_f32_16x16x32_bf16 v[62:65], v[22:25], v[198:201], v[62:65]
	v_mfma_f32_16x16x32_bf16 v[54:57], v[74:77], v[198:201], v[54:57]
	v_mfma_f32_16x16x32_bf16 v[42:45], v[22:25], v[210:213], v[42:45]
	v_mfma_f32_16x16x32_bf16 v[38:41], v[74:77], v[210:213], v[38:41]
	v_mfma_f32_16x16x32_bf16 v[14:17], v[22:25], v[218:221], v[14:17]
	v_mfma_f32_16x16x32_bf16 v[22:25], v[26:29], v[214:217], v[146:149]
	v_mfma_f32_16x16x32_bf16 v[26:29], v[78:81], v[182:185], v[50:53]
	v_mfma_f32_16x16x32_bf16 v[46:49], v[158:161], v[190:193], v[46:49]
	v_mfma_f32_16x16x32_bf16 v[34:37], v[82:85], v[198:201], v[34:37]
	v_mfma_f32_16x16x32_bf16 v[30:33], v[158:161], v[198:201], v[30:33]
	v_mfma_f32_16x16x32_bf16 v[18:21], v[82:85], v[210:213], v[18:21]
	v_mfma_f32_16x16x32_bf16 v[10:13], v[158:161], v[210:213], v[10:13]
	v_mfma_f32_16x16x32_bf16 v[6:9], v[82:85], v[218:221], v[6:9]
	v_mfma_f32_16x16x32_bf16 v[2:5], v[158:161], v[218:221], v[2:5]
	v_mfma_f32_16x16x32_bf16 v[22:25], v[74:77], v[218:221], v[22:25]
	v_mfma_f32_16x16x32_bf16 v[26:29], v[82:85], v[190:193], v[26:29]
	s_barrier
	s_add_i32 s72, 0, 0x18000
	v_add_u32_e32 v0, s72, v181
	s_add_i32 s73, 0, 0x1c000
	ds_read_b128 v[50:53], v0
	ds_read_b128 v[74:77], v0 offset:1024
	ds_read_b128 v[78:81], v0 offset:2048
	ds_read_b128 v[82:85], v0 offset:3072
	v_add_u32_e32 v0, s73, v181
	ds_read_b128 v[154:157], v0
	ds_read_b128 v[158:161], v0 offset:1024
	ds_read_b128 v[182:185], v0 offset:2048
	ds_read_b128 v[190:193], v0 offset:3072
	s_add_u32 s70, vcc_lo, 0x40000
	s_addc_u32 s71, vcc_hi, 0
	s_mov_b32 m0, s16
	v_lshl_add_u64 v[222:223], s[70:71], 0, v[162:163]
	ds_read_b128 v[86:89], v189 offset:32768
	ds_read_b128 v[146:149], v189 offset:33792
	ds_read_b128 v[194:197], v189 offset:34816
	ds_read_b128 v[198:201], v189 offset:35840
	ds_read_b128 v[202:205], v189 offset:36864
	ds_read_b128 v[210:213], v189 offset:37888
	ds_read_b128 v[214:217], v189 offset:38912
	ds_read_b128 v[218:221], v189 offset:39936
	global_load_lds_dwordx4 v[222:223], off
	v_lshl_add_u64 v[222:223], s[70:71], 0, v[166:167]
	s_mov_b32 m0, s17
	s_nop 0
	global_load_lds_dwordx4 v[222:223], off
	s_waitcnt vmcnt(8)
	s_waitcnt lgkmcnt(0)
	s_barrier
	s_waitcnt lgkmcnt(0)
	v_mfma_f32_16x16x32_bf16 v[150:153], v[50:53], v[86:89], v[150:153]
	v_mfma_f32_16x16x32_bf16 v[58:61], v[78:81], v[86:89], v[58:61]
	v_mfma_f32_16x16x32_bf16 v[142:145], v[154:157], v[86:89], v[142:145]
	v_mfma_f32_16x16x32_bf16 v[86:89], v[182:185], v[86:89], v[138:141]
	v_mfma_f32_16x16x32_bf16 v[138:141], v[190:193], v[146:149], v[86:89]
	v_mfma_f32_16x16x32_bf16 v[86:89], v[154:157], v[194:197], v[110:113]
	v_mfma_f32_16x16x32_bf16 v[110:113], v[158:161], v[198:201], v[86:89]
	v_mfma_f32_16x16x32_bf16 v[86:89], v[182:185], v[194:197], v[106:109]
	v_mfma_f32_16x16x32_bf16 v[106:109], v[190:193], v[198:201], v[86:89]
	v_mfma_f32_16x16x32_bf16 v[86:89], v[154:157], v[202:205], v[102:105]
	v_mfma_f32_16x16x32_bf16 v[102:105], v[158:161], v[210:213], v[86:89]
	v_mfma_f32_16x16x32_bf16 v[86:89], v[182:185], v[202:205], v[98:101]
	v_mfma_f32_16x16x32_bf16 v[98:101], v[190:193], v[210:213], v[86:89]
	v_mfma_f32_16x16x32_bf16 v[86:89], v[154:157], v[214:217], v[94:97]
	v_mfma_f32_16x16x32_bf16 v[126:129], v[50:53], v[194:197], v[126:129]
	v_mfma_f32_16x16x32_bf16 v[122:125], v[78:81], v[194:197], v[122:125]
	v_mfma_f32_16x16x32_bf16 v[118:121], v[50:53], v[202:205], v[118:121]
	v_mfma_f32_16x16x32_bf16 v[114:117], v[78:81], v[202:205], v[114:117]
	v_mfma_f32_16x16x32_bf16 v[134:137], v[50:53], v[214:217], v[134:137]
	v_mfma_f32_16x16x32_bf16 v[130:133], v[78:81], v[214:217], v[130:133]
	v_mfma_f32_16x16x32_bf16 v[94:97], v[158:161], v[218:221], v[86:89]
	v_mfma_f32_16x16x32_bf16 v[86:89], v[182:185], v[214:217], v[90:93]
	v_mfma_f32_16x16x32_bf16 v[150:153], v[74:77], v[146:149], v[150:153]
	v_mfma_f32_16x16x32_bf16 v[58:61], v[82:85], v[146:149], v[58:61]
	v_mfma_f32_16x16x32_bf16 v[126:129], v[74:77], v[198:201], v[126:129]
	v_mfma_f32_16x16x32_bf16 v[122:125], v[82:85], v[198:201], v[122:125]
	v_mfma_f32_16x16x32_bf16 v[118:121], v[74:77], v[210:213], v[118:121]
	v_mfma_f32_16x16x32_bf16 v[114:117], v[82:85], v[210:213], v[114:117]
	v_mfma_f32_16x16x32_bf16 v[134:137], v[74:77], v[218:221], v[134:137]
	v_mfma_f32_16x16x32_bf16 v[130:133], v[82:85], v[218:221], v[130:133]
	v_mfma_f32_16x16x32_bf16 v[142:145], v[158:161], v[146:149], v[142:145]
	v_mfma_f32_16x16x32_bf16 v[90:93], v[190:193], v[218:221], v[86:89]
	s_barrier
	s_add_i32 s70, s72, s29
	v_lshl_add_u64 v[86:87], v[174:175], 0, s[34:35]
	s_mov_b32 m0, s70
	ds_read_b128 v[194:197], v189 offset:49152
	ds_read_b128 v[198:201], v189 offset:50176
	ds_read_b128 v[202:205], v189 offset:51200
	ds_read_b128 v[210:213], v189 offset:52224
	ds_read_b128 v[214:217], v189 offset:53248
	ds_read_b128 v[218:221], v189 offset:54272
	ds_read_b128 v[222:225], v189 offset:55296
	ds_read_b128 v[242:245], v189 offset:56320
	global_load_lds_dwordx4 v[86:87], off
	s_add_i32 m0, s70, 0x2000
	s_add_u32 s70, s92, 0x40080
	v_lshl_add_u64 v[86:87], v[186:187], 0, s[34:35]
	s_addc_u32 s71, s93, 0
	s_add_i32 s72, s73, s29
	global_load_lds_dwordx4 v[86:87], off
	v_lshl_add_u64 v[86:87], s[70:71], 0, v[164:165]
	s_mov_b32 m0, s72
	s_nop 0
	global_load_lds_dwordx4 v[86:87], off
	v_lshl_add_u64 v[86:87], s[70:71], 0, v[168:169]
	s_add_i32 m0, s72, 0x2000
	s_nop 0
	global_load_lds_dwordx4 v[86:87], off
	v_lshl_add_u64 v[86:87], v[206:207], 0, s[34:35]
	s_mov_b32 m0, s19
	s_nop 0
	global_load_lds_dwordx4 v[86:87], off
	v_lshl_add_u64 v[86:87], v[226:227], 0, s[34:35]
	s_mov_b32 m0, s20
	s_nop 0
	global_load_lds_dwordx4 v[86:87], off
	s_waitcnt vmcnt(8)
	s_waitcnt lgkmcnt(0)
	s_barrier
	s_waitcnt lgkmcnt(0)
	v_mfma_f32_16x16x32_bf16 v[14:17], v[50:53], v[222:225], v[14:17]
	v_mfma_f32_16x16x32_bf16 v[86:89], v[74:77], v[242:245], v[14:17]
	v_mfma_f32_16x16x32_bf16 v[14:17], v[78:81], v[222:225], v[22:25]
	v_mfma_f32_16x16x32_bf16 v[146:149], v[82:85], v[242:245], v[14:17]
	v_mfma_f32_16x16x32_bf16 v[14:17], v[154:157], v[194:197], v[26:29]
	v_mfma_f32_16x16x32_bf16 v[70:73], v[50:53], v[194:197], v[70:73]
	v_mfma_f32_16x16x32_bf16 v[62:65], v[50:53], v[202:205], v[62:65]
	v_mfma_f32_16x16x32_bf16 v[42:45], v[50:53], v[214:217], v[42:45]
	v_mfma_f32_16x16x32_bf16 v[50:53], v[158:161], v[198:201], v[14:17]
	v_mfma_f32_16x16x32_bf16 v[14:17], v[182:185], v[194:197], v[46:49]
	v_mfma_f32_16x16x32_bf16 v[46:49], v[190:193], v[198:201], v[14:17]
	v_mfma_f32_16x16x32_bf16 v[14:17], v[154:157], v[202:205], v[34:37]
	v_mfma_f32_16x16x32_bf16 v[34:37], v[158:161], v[210:213], v[14:17]
	v_mfma_f32_16x16x32_bf16 v[14:17], v[182:185], v[202:205], v[30:33]
	v_mfma_f32_16x16x32_bf16 v[66:69], v[78:81], v[194:197], v[66:69]
	v_mfma_f32_16x16x32_bf16 v[54:57], v[78:81], v[202:205], v[54:57]
	v_mfma_f32_16x16x32_bf16 v[38:41], v[78:81], v[214:217], v[38:41]
	v_mfma_f32_16x16x32_bf16 v[30:33], v[190:193], v[210:213], v[14:17]
	v_mfma_f32_16x16x32_bf16 v[14:17], v[154:157], v[214:217], v[18:21]
	v_mfma_f32_16x16x32_bf16 v[10:13], v[182:185], v[214:217], v[10:13]
	v_mfma_f32_16x16x32_bf16 v[6:9], v[154:157], v[222:225], v[6:9]
	v_mfma_f32_16x16x32_bf16 v[2:5], v[182:185], v[222:225], v[2:5]
	v_mfma_f32_16x16x32_bf16 v[70:73], v[74:77], v[198:201], v[70:73]
	v_mfma_f32_16x16x32_bf16 v[66:69], v[82:85], v[198:201], v[66:69]
	v_mfma_f32_16x16x32_bf16 v[62:65], v[74:77], v[210:213], v[62:65]
	v_mfma_f32_16x16x32_bf16 v[54:57], v[82:85], v[210:213], v[54:57]
	v_mfma_f32_16x16x32_bf16 v[42:45], v[74:77], v[218:221], v[42:45]
	v_mfma_f32_16x16x32_bf16 v[38:41], v[82:85], v[218:221], v[38:41]
	v_mfma_f32_16x16x32_bf16 v[18:21], v[158:161], v[218:221], v[14:17]
	v_mfma_f32_16x16x32_bf16 v[10:13], v[190:193], v[218:221], v[10:13]
	v_mfma_f32_16x16x32_bf16 v[6:9], v[158:161], v[242:245], v[6:9]
	v_mfma_f32_16x16x32_bf16 v[2:5], v[190:193], v[242:245], v[2:5]
	s_barrier
	s_add_i32 s95, s95, 2
	s_add_u32 s42, s42, 0x100
	s_addc_u32 s43, s43, 0
	s_add_u32 s77, s77, 0x100
	s_addc_u32 s89, s89, 0
	s_cmp_gt_u32 s95, 13
	s_cbranch_scc0 .LBB0_243
	s_and_b64 vcc, exec, s[74:75]
	s_cbranch_vccz .LBB0_246
	s_barrier

.Lepi_st00:
	s_and_saveexec_b64 s[70:71], s[76:77]
	global_store_dwordx4 v175, v[250:253], s[72:73]
	s_or_b64 exec, exec, s[70:71]
	s_add_u32 s72, s84, 0x16000
	v_pk_mul_f32 v[202:203], v[118:119], v[78:79]
	s_addc_u32 s73, s85, 0
	v_pk_mul_f32 v[204:205], v[120:121], v[80:81]
	v_pk_mul_f32 v[242:243], v[218:219], s[98:99]
	v_pk_mul_f32 v[206:207], v[114:115], v[82:83]
	v_pk_mul_f32 v[244:245], v[220:221], s[98:99]
	v_pk_mul_f32 v[226:227], v[116:117], v[84:85]
	v_pk_mul_f32 v[246:247], v[222:223], s[98:99]
	v_fmac_f32_dpp v202, v118, v26 row_shr:1 row_mask:0xf bank_mask:0xf bound_ctrl:1
	v_pk_mul_f32 v[248:249], v[224:225], s[98:99]
	v_fmac_f32_dpp v203, v119, v27 row_shr:1 row_mask:0xf bank_mask:0xf bound_ctrl:1
	v_exp_f32_e32 v242, v242
	v_fmac_f32_dpp v204, v120, v28 row_shr:1 row_mask:0xf bank_mask:0xf bound_ctrl:1
	v_exp_f32_e32 v243, v243
	v_fmac_f32_dpp v205, v121, v29 row_shr:1 row_mask:0xf bank_mask:0xf bound_ctrl:1
	v_exp_f32_e32 v244, v244
	v_fmac_f32_dpp v206, v114, v74 row_shr:1 row_mask:0xf bank_mask:0xf bound_ctrl:1
	v_exp_f32_e32 v245, v245
	v_fmac_f32_dpp v207, v115, v75 row_shr:1 row_mask:0xf bank_mask:0xf bound_ctrl:1
	v_exp_f32_e32 v246, v246
	v_fmac_f32_dpp v226, v116, v76 row_shr:1 row_mask:0xf bank_mask:0xf bound_ctrl:1
	v_exp_f32_e32 v247, v247
	v_fmac_f32_dpp v227, v117, v77 row_shr:1 row_mask:0xf bank_mask:0xf bound_ctrl:1
	v_exp_f32_e32 v248, v248
	v_fmac_f32_dpp v202, v118, v14 row_shr:2 row_mask:0xf bank_mask:0xf bound_ctrl:1
	v_exp_f32_e32 v249, v249
	v_fmac_f32_dpp v203, v119, v15 row_shr:2 row_mask:0xf bank_mask:0xf bound_ctrl:1
	v_pk_add_f32 v[242:243], v[242:243], s[92:93]
	v_fmac_f32_dpp v204, v120, v16 row_shr:2 row_mask:0xf bank_mask:0xf bound_ctrl:1
	v_pk_add_f32 v[244:245], v[244:245], s[92:93]
	v_fmac_f32_dpp v205, v121, v17 row_shr:2 row_mask:0xf bank_mask:0xf bound_ctrl:1
	v_pk_add_f32 v[246:247], v[246:247], s[92:93]
	v_fmac_f32_dpp v206, v114, v22 row_shr:2 row_mask:0xf bank_mask:0xf bound_ctrl:1
	v_pk_add_f32 v[248:249], v[248:249], s[92:93]
	v_fmac_f32_dpp v207, v115, v23 row_shr:2 row_mask:0xf bank_mask:0xf bound_ctrl:1
	v_rcp_f32_e32 v242, v242
	v_fmac_f32_dpp v226, v116, v24 row_shr:2 row_mask:0xf bank_mask:0xf bound_ctrl:1
	v_rcp_f32_e32 v243, v243
	v_fmac_f32_dpp v227, v117, v25 row_shr:2 row_mask:0xf bank_mask:0xf bound_ctrl:1
	v_rcp_f32_e32 v244, v244
	v_fmac_f32_dpp v202, v126, v154 row_ror:1 row_mask:0xf bank_mask:0xf bound_ctrl:1
	v_rcp_f32_e32 v245, v245
	v_fmac_f32_dpp v203, v127, v155 row_ror:1 row_mask:0xf bank_mask:0xf bound_ctrl:1
	v_rcp_f32_e32 v246, v246
	v_fmac_f32_dpp v204, v128, v156 row_ror:1 row_mask:0xf bank_mask:0xf bound_ctrl:1
	v_rcp_f32_e32 v247, v247
	v_fmac_f32_dpp v205, v129, v157 row_ror:1 row_mask:0xf bank_mask:0xf bound_ctrl:1
	v_rcp_f32_e32 v248, v248
	v_fmac_f32_dpp v206, v122, v158 row_ror:1 row_mask:0xf bank_mask:0xf bound_ctrl:1
	v_rcp_f32_e32 v249, v249
	v_fmac_f32_dpp v207, v123, v159 row_ror:1 row_mask:0xf bank_mask:0xf bound_ctrl:1
	v_pk_mul_f32 v[218:219], v[218:219], v[242:243]
	v_fmac_f32_dpp v226, v124, v160 row_ror:1 row_mask:0xf bank_mask:0xf bound_ctrl:1
	v_pk_mul_f32 v[220:221], v[220:221], v[244:245]
	v_fmac_f32_dpp v227, v125, v161 row_ror:1 row_mask:0xf bank_mask:0xf bound_ctrl:1
	v_pk_mul_f32 v[222:223], v[222:223], v[246:247]
	v_fmac_f32_dpp v202, v126, v182 row_ror:2 row_mask:0xf bank_mask:0xf bound_ctrl:1
	v_pk_mul_f32 v[224:225], v[224:225], v[248:249]
	v_fmac_f32_dpp v203, v127, v183 row_ror:2 row_mask:0xf bank_mask:0xf bound_ctrl:1
	v_pk_mul_f32 v[110:111], v[110:111], v[218:219]
	v_fmac_f32_dpp v204, v128, v184 row_ror:2 row_mask:0xf bank_mask:0xf bound_ctrl:1
	v_pk_mul_f32 v[112:113], v[112:113], v[220:221]
	v_fmac_f32_dpp v205, v129, v185 row_ror:2 row_mask:0xf bank_mask:0xf bound_ctrl:1
	v_pk_mul_f32 v[106:107], v[106:107], v[222:223]
	v_fmac_f32_dpp v206, v122, v190 row_ror:2 row_mask:0xf bank_mask:0xf bound_ctrl:1
	v_pk_mul_f32 v[108:109], v[108:109], v[224:225]
	v_fmac_f32_dpp v207, v123, v191 row_ror:2 row_mask:0xf bank_mask:0xf bound_ctrl:1
	v_cvt_pk_bf16_f32 v250, v110, v111
	v_fmac_f32_dpp v226, v124, v192 row_ror:2 row_mask:0xf bank_mask:0xf bound_ctrl:1
	v_cvt_pk_bf16_f32 v251, v112, v113
	v_fmac_f32_dpp v227, v125, v193 row_ror:2 row_mask:0xf bank_mask:0xf bound_ctrl:1
	v_cvt_pk_bf16_f32 v252, v106, v107
	v_cvt_pk_bf16_f32 v253, v108, v109
	global_store_dwordx4 v175, v[250:253], s[72:73]
	s_add_u32 s72, s84, 0x2c000
	v_pk_mul_f32 v[218:219], v[134:135], v[78:79]
	s_addc_u32 s73, s85, 0
	v_pk_mul_f32 v[220:221], v[136:137], v[80:81]
	v_pk_mul_f32 v[242:243], v[202:203], s[98:99]
	v_pk_mul_f32 v[222:223], v[130:131], v[82:83]
	v_pk_mul_f32 v[244:245], v[204:205], s[98:99]
	v_pk_mul_f32 v[224:225], v[132:133], v[84:85]
	v_pk_mul_f32 v[246:247], v[206:207], s[98:99]
	v_fmac_f32_dpp v218, v134, v26 row_shr:1 row_mask:0xf bank_mask:0xf bound_ctrl:1
	v_pk_mul_f32 v[248:249], v[226:227], s[98:99]
	v_fmac_f32_dpp v219, v135, v27 row_shr:1 row_mask:0xf bank_mask:0xf bound_ctrl:1
	v_exp_f32_e32 v242, v242
	v_fmac_f32_dpp v220, v136, v28 row_shr:1 row_mask:0xf bank_mask:0xf bound_ctrl:1
	v_exp_f32_e32 v243, v243
	v_fmac_f32_dpp v221, v137, v29 row_shr:1 row_mask:0xf bank_mask:0xf bound_ctrl:1
	v_exp_f32_e32 v244, v244
	v_fmac_f32_dpp v222, v130, v74 row_shr:1 row_mask:0xf bank_mask:0xf bound_ctrl:1
	v_exp_f32_e32 v245, v245
	v_fmac_f32_dpp v223, v131, v75 row_shr:1 row_mask:0xf bank_mask:0xf bound_ctrl:1
	v_exp_f32_e32 v246, v246
	v_fmac_f32_dpp v224, v132, v76 row_shr:1 row_mask:0xf bank_mask:0xf bound_ctrl:1
	v_exp_f32_e32 v247, v247
	v_fmac_f32_dpp v225, v133, v77 row_shr:1 row_mask:0xf bank_mask:0xf bound_ctrl:1
	v_exp_f32_e32 v248, v248
	v_fmac_f32_dpp v218, v134, v14 row_shr:2 row_mask:0xf bank_mask:0xf bound_ctrl:1
	v_exp_f32_e32 v249, v249
	v_fmac_f32_dpp v219, v135, v15 row_shr:2 row_mask:0xf bank_mask:0xf bound_ctrl:1
	v_pk_add_f32 v[242:243], v[242:243], s[92:93]
	v_fmac_f32_dpp v220, v136, v16 row_shr:2 row_mask:0xf bank_mask:0xf bound_ctrl:1
	v_pk_add_f32 v[244:245], v[244:245], s[92:93]
	v_fmac_f32_dpp v221, v137, v17 row_shr:2 row_mask:0xf bank_mask:0xf bound_ctrl:1
	v_pk_add_f32 v[246:247], v[246:247], s[92:93]
	v_fmac_f32_dpp v222, v130, v22 row_shr:2 row_mask:0xf bank_mask:0xf bound_ctrl:1
	v_pk_add_f32 v[248:249], v[248:249], s[92:93]
	v_fmac_f32_dpp v223, v131, v23 row_shr:2 row_mask:0xf bank_mask:0xf bound_ctrl:1
	v_rcp_f32_e32 v242, v242
	v_fmac_f32_dpp v224, v132, v24 row_shr:2 row_mask:0xf bank_mask:0xf bound_ctrl:1
	v_rcp_f32_e32 v243, v243
	v_fmac_f32_dpp v225, v133, v25 row_shr:2 row_mask:0xf bank_mask:0xf bound_ctrl:1
	v_rcp_f32_e32 v244, v244
	v_fmac_f32_dpp v218, v118, v154 row_ror:1 row_mask:0xf bank_mask:0xf bound_ctrl:1
	v_rcp_f32_e32 v245, v245
	v_fmac_f32_dpp v219, v119, v155 row_ror:1 row_mask:0xf bank_mask:0xf bound_ctrl:1
	v_rcp_f32_e32 v246, v246
	v_fmac_f32_dpp v220, v120, v156 row_ror:1 row_mask:0xf bank_mask:0xf bound_ctrl:1
	v_rcp_f32_e32 v247, v247
	v_fmac_f32_dpp v221, v121, v157 row_ror:1 row_mask:0xf bank_mask:0xf bound_ctrl:1
	v_rcp_f32_e32 v248, v248
	v_fmac_f32_dpp v222, v114, v158 row_ror:1 row_mask:0xf bank_mask:0xf bound_ctrl:1
	v_rcp_f32_e32 v249, v249
	v_fmac_f32_dpp v223, v115, v159 row_ror:1 row_mask:0xf bank_mask:0xf bound_ctrl:1
	v_pk_mul_f32 v[202:203], v[202:203], v[242:243]
	v_fmac_f32_dpp v224, v116, v160 row_ror:1 row_mask:0xf bank_mask:0xf bound_ctrl:1
	v_pk_mul_f32 v[204:205], v[204:205], v[244:245]
	v_fmac_f32_dpp v225, v117, v161 row_ror:1 row_mask:0xf bank_mask:0xf bound_ctrl:1
	v_pk_mul_f32 v[206:207], v[206:207], v[246:247]
	v_fmac_f32_dpp v218, v118, v182 row_ror:2 row_mask:0xf bank_mask:0xf bound_ctrl:1
	v_pk_mul_f32 v[226:227], v[226:227], v[248:249]
	v_fmac_f32_dpp v219, v119, v183 row_ror:2 row_mask:0xf bank_mask:0xf bound_ctrl:1
	v_pk_mul_f32 v[102:103], v[102:103], v[202:203]
	v_fmac_f32_dpp v220, v120, v184 row_ror:2 row_mask:0xf bank_mask:0xf bound_ctrl:1
	v_pk_mul_f32 v[104:105], v[104:105], v[204:205]
	v_fmac_f32_dpp v221, v121, v185 row_ror:2 row_mask:0xf bank_mask:0xf bound_ctrl:1
	v_pk_mul_f32 v[98:99], v[98:99], v[206:207]
	v_fmac_f32_dpp v222, v114, v190 row_ror:2 row_mask:0xf bank_mask:0xf bound_ctrl:1
	v_pk_mul_f32 v[100:101], v[100:101], v[226:227]
	v_fmac_f32_dpp v223, v115, v191 row_ror:2 row_mask:0xf bank_mask:0xf bound_ctrl:1
	v_cvt_pk_bf16_f32 v250, v102, v103
	v_fmac_f32_dpp v224, v116, v192 row_ror:2 row_mask:0xf bank_mask:0xf bound_ctrl:1
	v_cvt_pk_bf16_f32 v251, v104, v105
	v_fmac_f32_dpp v225, v117, v193 row_ror:2 row_mask:0xf bank_mask:0xf bound_ctrl:1
	v_cvt_pk_bf16_f32 v252, v98, v99
	v_cvt_pk_bf16_f32 v253, v100, v101
	global_store_dwordx4 v175, v[250:253], s[72:73]
	s_add_u32 s72, s84, 0x42000
	v_pk_mul_f32 v[202:203], v[70:71], v[78:79]
	s_addc_u32 s73, s85, 0
	v_pk_mul_f32 v[204:205], v[72:73], v[80:81]
	v_pk_mul_f32 v[242:243], v[218:219], s[98:99]
	v_pk_mul_f32 v[206:207], v[66:67], v[82:83]
	v_pk_mul_f32 v[244:245], v[220:221], s[98:99]
	v_pk_mul_f32 v[226:227], v[68:69], v[84:85]
	v_pk_mul_f32 v[246:247], v[222:223], s[98:99]
	v_fmac_f32_dpp v202, v70, v26 row_shr:1 row_mask:0xf bank_mask:0xf bound_ctrl:1
	v_pk_mul_f32 v[248:249], v[224:225], s[98:99]
	v_fmac_f32_dpp v203, v71, v27 row_shr:1 row_mask:0xf bank_mask:0xf bound_ctrl:1
	v_exp_f32_e32 v242, v242
	v_fmac_f32_dpp v204, v72, v28 row_shr:1 row_mask:0xf bank_mask:0xf bound_ctrl:1
	v_exp_f32_e32 v243, v243
	v_fmac_f32_dpp v205, v73, v29 row_shr:1 row_mask:0xf bank_mask:0xf bound_ctrl:1
	v_exp_f32_e32 v244, v244
	v_fmac_f32_dpp v206, v66, v74 row_shr:1 row_mask:0xf bank_mask:0xf bound_ctrl:1
	v_exp_f32_e32 v245, v245
	v_fmac_f32_dpp v207, v67, v75 row_shr:1 row_mask:0xf bank_mask:0xf bound_ctrl:1
	v_exp_f32_e32 v246, v246
	v_fmac_f32_dpp v226, v68, v76 row_shr:1 row_mask:0xf bank_mask:0xf bound_ctrl:1
	v_exp_f32_e32 v247, v247
	v_fmac_f32_dpp v227, v69, v77 row_shr:1 row_mask:0xf bank_mask:0xf bound_ctrl:1
	v_exp_f32_e32 v248, v248
	v_fmac_f32_dpp v202, v70, v14 row_shr:2 row_mask:0xf bank_mask:0xf bound_ctrl:1
	v_exp_f32_e32 v249, v249
	v_fmac_f32_dpp v203, v71, v15 row_shr:2 row_mask:0xf bank_mask:0xf bound_ctrl:1
	v_pk_add_f32 v[242:243], v[242:243], s[92:93]
	v_fmac_f32_dpp v204, v72, v16 row_shr:2 row_mask:0xf bank_mask:0xf bound_ctrl:1
	v_pk_add_f32 v[244:245], v[244:245], s[92:93]
	v_fmac_f32_dpp v205, v73, v17 row_shr:2 row_mask:0xf bank_mask:0xf bound_ctrl:1
	v_pk_add_f32 v[246:247], v[246:247], s[92:93]
	v_fmac_f32_dpp v206, v66, v22 row_shr:2 row_mask:0xf bank_mask:0xf bound_ctrl:1
	v_pk_add_f32 v[248:249], v[248:249], s[92:93]
	v_fmac_f32_dpp v207, v67, v23 row_shr:2 row_mask:0xf bank_mask:0xf bound_ctrl:1
	v_rcp_f32_e32 v242, v242
	v_fmac_f32_dpp v226, v68, v24 row_shr:2 row_mask:0xf bank_mask:0xf bound_ctrl:1
	v_rcp_f32_e32 v243, v243
	v_fmac_f32_dpp v227, v69, v25 row_shr:2 row_mask:0xf bank_mask:0xf bound_ctrl:1
	v_rcp_f32_e32 v244, v244
	v_fmac_f32_dpp v202, v210, v154 row_ror:1 row_mask:0xf bank_mask:0xf bound_ctrl:1
	v_rcp_f32_e32 v245, v245
	v_fmac_f32_dpp v203, v211, v155 row_ror:1 row_mask:0xf bank_mask:0xf bound_ctrl:1
	v_rcp_f32_e32 v246, v246
	v_fmac_f32_dpp v204, v212, v156 row_ror:1 row_mask:0xf bank_mask:0xf bound_ctrl:1
	v_rcp_f32_e32 v247, v247
	v_fmac_f32_dpp v205, v213, v157 row_ror:1 row_mask:0xf bank_mask:0xf bound_ctrl:1
	v_rcp_f32_e32 v248, v248
	v_fmac_f32_dpp v206, v214, v158 row_ror:1 row_mask:0xf bank_mask:0xf bound_ctrl:1
	v_rcp_f32_e32 v249, v249
	v_fmac_f32_dpp v207, v215, v159 row_ror:1 row_mask:0xf bank_mask:0xf bound_ctrl:1
	v_pk_mul_f32 v[218:219], v[218:219], v[242:243]
	v_fmac_f32_dpp v226, v216, v160 row_ror:1 row_mask:0xf bank_mask:0xf bound_ctrl:1
	v_pk_mul_f32 v[220:221], v[220:221], v[244:245]
	v_fmac_f32_dpp v227, v217, v161 row_ror:1 row_mask:0xf bank_mask:0xf bound_ctrl:1
	v_pk_mul_f32 v[222:223], v[222:223], v[246:247]
	v_fmac_f32_dpp v202, v210, v182 row_ror:2 row_mask:0xf bank_mask:0xf bound_ctrl:1
	v_pk_mul_f32 v[224:225], v[224:225], v[248:249]
	v_fmac_f32_dpp v203, v211, v183 row_ror:2 row_mask:0xf bank_mask:0xf bound_ctrl:1
	v_pk_mul_f32 v[94:95], v[94:95], v[218:219]
	v_fmac_f32_dpp v204, v212, v184 row_ror:2 row_mask:0xf bank_mask:0xf bound_ctrl:1
	v_pk_mul_f32 v[96:97], v[96:97], v[220:221]
	v_fmac_f32_dpp v205, v213, v185 row_ror:2 row_mask:0xf bank_mask:0xf bound_ctrl:1
	v_pk_mul_f32 v[90:91], v[90:91], v[222:223]
	v_fmac_f32_dpp v206, v214, v190 row_ror:2 row_mask:0xf bank_mask:0xf bound_ctrl:1
	v_pk_mul_f32 v[92:93], v[92:93], v[224:225]
	v_fmac_f32_dpp v207, v215, v191 row_ror:2 row_mask:0xf bank_mask:0xf bound_ctrl:1
	v_cvt_pk_bf16_f32 v250, v94, v95
	v_fmac_f32_dpp v226, v216, v192 row_ror:2 row_mask:0xf bank_mask:0xf bound_ctrl:1
	v_cvt_pk_bf16_f32 v251, v96, v97
	v_fmac_f32_dpp v227, v217, v193 row_ror:2 row_mask:0xf bank_mask:0xf bound_ctrl:1
	v_cvt_pk_bf16_f32 v252, v90, v91
	v_cvt_pk_bf16_f32 v253, v92, v93
	global_store_dwordx4 v175, v[250:253], s[72:73]
	s_add_u32 s72, s84, 0xb0000
	v_pk_mul_f32 v[218:219], v[62:63], v[78:79]
	s_addc_u32 s73, s85, 0
	v_pk_mul_f32 v[220:221], v[64:65], v[80:81]
	v_pk_mul_f32 v[242:243], v[202:203], s[98:99]
	v_pk_mul_f32 v[222:223], v[54:55], v[82:83]
	v_pk_mul_f32 v[244:245], v[204:205], s[98:99]
	v_pk_mul_f32 v[224:225], v[56:57], v[84:85]
	v_pk_mul_f32 v[246:247], v[206:207], s[98:99]
	v_fmac_f32_dpp v218, v62, v26 row_shr:1 row_mask:0xf bank_mask:0xf bound_ctrl:1
	v_pk_mul_f32 v[248:249], v[226:227], s[98:99]
	v_fmac_f32_dpp v219, v63, v27 row_shr:1 row_mask:0xf bank_mask:0xf bound_ctrl:1
	v_exp_f32_e32 v242, v242
	v_fmac_f32_dpp v220, v64, v28 row_shr:1 row_mask:0xf bank_mask:0xf bound_ctrl:1
	v_exp_f32_e32 v243, v243
	v_fmac_f32_dpp v221, v65, v29 row_shr:1 row_mask:0xf bank_mask:0xf bound_ctrl:1
	v_exp_f32_e32 v244, v244
	v_fmac_f32_dpp v222, v54, v74 row_shr:1 row_mask:0xf bank_mask:0xf bound_ctrl:1
	v_exp_f32_e32 v245, v245
	v_fmac_f32_dpp v223, v55, v75 row_shr:1 row_mask:0xf bank_mask:0xf bound_ctrl:1
	v_exp_f32_e32 v246, v246
	v_fmac_f32_dpp v224, v56, v76 row_shr:1 row_mask:0xf bank_mask:0xf bound_ctrl:1
	v_exp_f32_e32 v247, v247
	v_fmac_f32_dpp v225, v57, v77 row_shr:1 row_mask:0xf bank_mask:0xf bound_ctrl:1
	v_exp_f32_e32 v248, v248
	v_fmac_f32_dpp v218, v62, v14 row_shr:2 row_mask:0xf bank_mask:0xf bound_ctrl:1
	v_exp_f32_e32 v249, v249
	v_fmac_f32_dpp v219, v63, v15 row_shr:2 row_mask:0xf bank_mask:0xf bound_ctrl:1
	v_pk_add_f32 v[242:243], v[242:243], s[92:93]
	v_fmac_f32_dpp v220, v64, v16 row_shr:2 row_mask:0xf bank_mask:0xf bound_ctrl:1
	v_pk_add_f32 v[244:245], v[244:245], s[92:93]
	v_fmac_f32_dpp v221, v65, v17 row_shr:2 row_mask:0xf bank_mask:0xf bound_ctrl:1
	v_pk_add_f32 v[246:247], v[246:247], s[92:93]
	v_fmac_f32_dpp v222, v54, v22 row_shr:2 row_mask:0xf bank_mask:0xf bound_ctrl:1
	v_pk_add_f32 v[248:249], v[248:249], s[92:93]
	v_fmac_f32_dpp v223, v55, v23 row_shr:2 row_mask:0xf bank_mask:0xf bound_ctrl:1
	v_rcp_f32_e32 v242, v242
	v_fmac_f32_dpp v224, v56, v24 row_shr:2 row_mask:0xf bank_mask:0xf bound_ctrl:1
	v_rcp_f32_e32 v243, v243
	v_fmac_f32_dpp v225, v57, v25 row_shr:2 row_mask:0xf bank_mask:0xf bound_ctrl:1
	v_rcp_f32_e32 v244, v244
	v_fmac_f32_dpp v218, v70, v154 row_ror:1 row_mask:0xf bank_mask:0xf bound_ctrl:1
	v_rcp_f32_e32 v245, v245
	v_fmac_f32_dpp v219, v71, v155 row_ror:1 row_mask:0xf bank_mask:0xf bound_ctrl:1
	v_rcp_f32_e32 v246, v246
	v_fmac_f32_dpp v220, v72, v156 row_ror:1 row_mask:0xf bank_mask:0xf bound_ctrl:1
	v_rcp_f32_e32 v247, v247
	v_fmac_f32_dpp v221, v73, v157 row_ror:1 row_mask:0xf bank_mask:0xf bound_ctrl:1
	v_rcp_f32_e32 v248, v248
	v_fmac_f32_dpp v222, v66, v158 row_ror:1 row_mask:0xf bank_mask:0xf bound_ctrl:1
	v_rcp_f32_e32 v249, v249
	v_fmac_f32_dpp v223, v67, v159 row_ror:1 row_mask:0xf bank_mask:0xf bound_ctrl:1
	v_pk_mul_f32 v[202:203], v[202:203], v[242:243]
	v_fmac_f32_dpp v224, v68, v160 row_ror:1 row_mask:0xf bank_mask:0xf bound_ctrl:1
	v_pk_mul_f32 v[204:205], v[204:205], v[244:245]
	v_fmac_f32_dpp v225, v69, v161 row_ror:1 row_mask:0xf bank_mask:0xf bound_ctrl:1
	v_pk_mul_f32 v[206:207], v[206:207], v[246:247]
	v_fmac_f32_dpp v218, v70, v182 row_ror:2 row_mask:0xf bank_mask:0xf bound_ctrl:1
	v_pk_mul_f32 v[226:227], v[226:227], v[248:249]
	v_fmac_f32_dpp v219, v71, v183 row_ror:2 row_mask:0xf bank_mask:0xf bound_ctrl:1
	v_pk_mul_f32 v[50:51], v[50:51], v[202:203]
	v_fmac_f32_dpp v220, v72, v184 row_ror:2 row_mask:0xf bank_mask:0xf bound_ctrl:1
	v_pk_mul_f32 v[52:53], v[52:53], v[204:205]
	v_fmac_f32_dpp v221, v73, v185 row_ror:2 row_mask:0xf bank_mask:0xf bound_ctrl:1
	v_pk_mul_f32 v[46:47], v[46:47], v[206:207]
	v_fmac_f32_dpp v222, v66, v190 row_ror:2 row_mask:0xf bank_mask:0xf bound_ctrl:1
	v_pk_mul_f32 v[48:49], v[48:49], v[226:227]
	v_fmac_f32_dpp v223, v67, v191 row_ror:2 row_mask:0xf bank_mask:0xf bound_ctrl:1
	v_cvt_pk_bf16_f32 v250, v50, v51
	v_fmac_f32_dpp v224, v68, v192 row_ror:2 row_mask:0xf bank_mask:0xf bound_ctrl:1
	v_cvt_pk_bf16_f32 v251, v52, v53
	v_fmac_f32_dpp v225, v69, v193 row_ror:2 row_mask:0xf bank_mask:0xf bound_ctrl:1
	v_cvt_pk_bf16_f32 v252, v46, v47
	v_cvt_pk_bf16_f32 v253, v48, v49
	global_store_dwordx4 v175, v[250:253], s[72:73]
	s_add_u32 s72, s84, 0xc6000
	v_pk_mul_f32 v[202:203], v[42:43], v[78:79]
	s_addc_u32 s73, s85, 0
	v_pk_mul_f32 v[204:205], v[44:45], v[80:81]
	v_pk_mul_f32 v[242:243], v[218:219], s[98:99]
	v_pk_mul_f32 v[206:207], v[38:39], v[82:83]
	v_pk_mul_f32 v[244:245], v[220:221], s[98:99]
	v_pk_mul_f32 v[226:227], v[40:41], v[84:85]
	v_pk_mul_f32 v[246:247], v[222:223], s[98:99]
	v_fmac_f32_dpp v202, v42, v26 row_shr:1 row_mask:0xf bank_mask:0xf bound_ctrl:1
	v_pk_mul_f32 v[248:249], v[224:225], s[98:99]
	v_fmac_f32_dpp v203, v43, v27 row_shr:1 row_mask:0xf bank_mask:0xf bound_ctrl:1
	v_exp_f32_e32 v242, v242
	v_fmac_f32_dpp v204, v44, v28 row_shr:1 row_mask:0xf bank_mask:0xf bound_ctrl:1
	v_exp_f32_e32 v243, v243
	v_fmac_f32_dpp v205, v45, v29 row_shr:1 row_mask:0xf bank_mask:0xf bound_ctrl:1
	v_exp_f32_e32 v244, v244
	v_fmac_f32_dpp v206, v38, v74 row_shr:1 row_mask:0xf bank_mask:0xf bound_ctrl:1
	v_exp_f32_e32 v245, v245
	v_fmac_f32_dpp v207, v39, v75 row_shr:1 row_mask:0xf bank_mask:0xf bound_ctrl:1
	v_exp_f32_e32 v246, v246
	v_fmac_f32_dpp v226, v40, v76 row_shr:1 row_mask:0xf bank_mask:0xf bound_ctrl:1
	v_exp_f32_e32 v247, v247
	v_fmac_f32_dpp v227, v41, v77 row_shr:1 row_mask:0xf bank_mask:0xf bound_ctrl:1
	v_exp_f32_e32 v248, v248
	v_fmac_f32_dpp v202, v42, v14 row_shr:2 row_mask:0xf bank_mask:0xf bound_ctrl:1
	v_exp_f32_e32 v249, v249
	v_fmac_f32_dpp v203, v43, v15 row_shr:2 row_mask:0xf bank_mask:0xf bound_ctrl:1
	v_pk_add_f32 v[242:243], v[242:243], s[92:93]
	v_fmac_f32_dpp v204, v44, v16 row_shr:2 row_mask:0xf bank_mask:0xf bound_ctrl:1
	v_pk_add_f32 v[244:245], v[244:245], s[92:93]
	v_fmac_f32_dpp v205, v45, v17 row_shr:2 row_mask:0xf bank_mask:0xf bound_ctrl:1
	v_pk_add_f32 v[246:247], v[246:247], s[92:93]
	v_fmac_f32_dpp v206, v38, v22 row_shr:2 row_mask:0xf bank_mask:0xf bound_ctrl:1
	v_pk_add_f32 v[248:249], v[248:249], s[92:93]
	v_fmac_f32_dpp v207, v39, v23 row_shr:2 row_mask:0xf bank_mask:0xf bound_ctrl:1
	v_rcp_f32_e32 v242, v242
	v_fmac_f32_dpp v226, v40, v24 row_shr:2 row_mask:0xf bank_mask:0xf bound_ctrl:1
	v_rcp_f32_e32 v243, v243
	v_fmac_f32_dpp v227, v41, v25 row_shr:2 row_mask:0xf bank_mask:0xf bound_ctrl:1
	v_rcp_f32_e32 v244, v244
	v_fmac_f32_dpp v202, v62, v154 row_ror:1 row_mask:0xf bank_mask:0xf bound_ctrl:1
	v_rcp_f32_e32 v245, v245
	v_fmac_f32_dpp v203, v63, v155 row_ror:1 row_mask:0xf bank_mask:0xf bound_ctrl:1
	v_rcp_f32_e32 v246, v246
	v_fmac_f32_dpp v204, v64, v156 row_ror:1 row_mask:0xf bank_mask:0xf bound_ctrl:1
	v_rcp_f32_e32 v247, v247
	v_fmac_f32_dpp v205, v65, v157 row_ror:1 row_mask:0xf bank_mask:0xf bound_ctrl:1
	v_rcp_f32_e32 v248, v248
	v_fmac_f32_dpp v206, v54, v158 row_ror:1 row_mask:0xf bank_mask:0xf bound_ctrl:1
	v_rcp_f32_e32 v249, v249
	v_fmac_f32_dpp v207, v55, v159 row_ror:1 row_mask:0xf bank_mask:0xf bound_ctrl:1
	v_pk_mul_f32 v[218:219], v[218:219], v[242:243]
	v_fmac_f32_dpp v226, v56, v160 row_ror:1 row_mask:0xf bank_mask:0xf bound_ctrl:1
	v_pk_mul_f32 v[220:221], v[220:221], v[244:245]
	v_fmac_f32_dpp v227, v57, v161 row_ror:1 row_mask:0xf bank_mask:0xf bound_ctrl:1
	v_pk_mul_f32 v[222:223], v[222:223], v[246:247]
	v_fmac_f32_dpp v202, v62, v182 row_ror:2 row_mask:0xf bank_mask:0xf bound_ctrl:1
	v_pk_mul_f32 v[224:225], v[224:225], v[248:249]
	v_fmac_f32_dpp v203, v63, v183 row_ror:2 row_mask:0xf bank_mask:0xf bound_ctrl:1
	v_pk_mul_f32 v[34:35], v[34:35], v[218:219]
	v_fmac_f32_dpp v204, v64, v184 row_ror:2 row_mask:0xf bank_mask:0xf bound_ctrl:1
	v_pk_mul_f32 v[36:37], v[36:37], v[220:221]
	v_fmac_f32_dpp v205, v65, v185 row_ror:2 row_mask:0xf bank_mask:0xf bound_ctrl:1
	v_pk_mul_f32 v[30:31], v[30:31], v[222:223]
	v_fmac_f32_dpp v206, v54, v190 row_ror:2 row_mask:0xf bank_mask:0xf bound_ctrl:1
	v_pk_mul_f32 v[32:33], v[32:33], v[224:225]
	v_fmac_f32_dpp v207, v55, v191 row_ror:2 row_mask:0xf bank_mask:0xf bound_ctrl:1
	v_cvt_pk_bf16_f32 v250, v34, v35
	v_fmac_f32_dpp v226, v56, v192 row_ror:2 row_mask:0xf bank_mask:0xf bound_ctrl:1
	v_cvt_pk_bf16_f32 v251, v36, v37
	v_fmac_f32_dpp v227, v57, v193 row_ror:2 row_mask:0xf bank_mask:0xf bound_ctrl:1
	v_cvt_pk_bf16_f32 v252, v30, v31
	v_cvt_pk_bf16_f32 v253, v32, v33
	global_store_dwordx4 v175, v[250:253], s[72:73]
	s_add_u32 s72, s84, 0xdc000
	v_pk_mul_f32 v[218:219], v[86:87], v[78:79]
	s_addc_u32 s73, s85, 0
	v_pk_mul_f32 v[220:221], v[88:89], v[80:81]
	v_pk_mul_f32 v[242:243], v[202:203], s[98:99]
	v_pk_mul_f32 v[222:223], v[146:147], v[82:83]
	v_pk_mul_f32 v[244:245], v[204:205], s[98:99]
	v_pk_mul_f32 v[224:225], v[148:149], v[84:85]
	v_pk_mul_f32 v[246:247], v[206:207], s[98:99]
	v_fmac_f32_dpp v218, v86, v26 row_shr:1 row_mask:0xf bank_mask:0xf bound_ctrl:1
	v_pk_mul_f32 v[248:249], v[226:227], s[98:99]
	v_fmac_f32_dpp v219, v87, v27 row_shr:1 row_mask:0xf bank_mask:0xf bound_ctrl:1
	v_exp_f32_e32 v242, v242
	v_fmac_f32_dpp v220, v88, v28 row_shr:1 row_mask:0xf bank_mask:0xf bound_ctrl:1
	v_exp_f32_e32 v243, v243
	v_fmac_f32_dpp v221, v89, v29 row_shr:1 row_mask:0xf bank_mask:0xf bound_ctrl:1
	v_exp_f32_e32 v244, v244
	v_fmac_f32_dpp v222, v146, v74 row_shr:1 row_mask:0xf bank_mask:0xf bound_ctrl:1
	v_exp_f32_e32 v245, v245
	v_fmac_f32_dpp v223, v147, v75 row_shr:1 row_mask:0xf bank_mask:0xf bound_ctrl:1
	v_exp_f32_e32 v246, v246
	v_fmac_f32_dpp v224, v148, v76 row_shr:1 row_mask:0xf bank_mask:0xf bound_ctrl:1
	v_exp_f32_e32 v247, v247
	v_fmac_f32_dpp v225, v149, v77 row_shr:1 row_mask:0xf bank_mask:0xf bound_ctrl:1
	v_exp_f32_e32 v248, v248
	v_fmac_f32_dpp v218, v86, v14 row_shr:2 row_mask:0xf bank_mask:0xf bound_ctrl:1
	v_exp_f32_e32 v249, v249
	v_fmac_f32_dpp v219, v87, v15 row_shr:2 row_mask:0xf bank_mask:0xf bound_ctrl:1
	v_pk_add_f32 v[242:243], v[242:243], s[92:93]
	v_fmac_f32_dpp v220, v88, v16 row_shr:2 row_mask:0xf bank_mask:0xf bound_ctrl:1
	v_pk_add_f32 v[244:245], v[244:245], s[92:93]
	v_fmac_f32_dpp v221, v89, v17 row_shr:2 row_mask:0xf bank_mask:0xf bound_ctrl:1
	v_pk_add_f32 v[246:247], v[246:247], s[92:93]
	v_fmac_f32_dpp v222, v146, v22 row_shr:2 row_mask:0xf bank_mask:0xf bound_ctrl:1
	v_pk_add_f32 v[248:249], v[248:249], s[92:93]
	v_fmac_f32_dpp v223, v147, v23 row_shr:2 row_mask:0xf bank_mask:0xf bound_ctrl:1
	v_rcp_f32_e32 v242, v242
	v_fmac_f32_dpp v224, v148, v24 row_shr:2 row_mask:0xf bank_mask:0xf bound_ctrl:1
	v_rcp_f32_e32 v243, v243
	v_fmac_f32_dpp v225, v149, v25 row_shr:2 row_mask:0xf bank_mask:0xf bound_ctrl:1
	v_rcp_f32_e32 v244, v244
	v_fmac_f32_dpp v218, v42, v154 row_ror:1 row_mask:0xf bank_mask:0xf bound_ctrl:1
	v_rcp_f32_e32 v245, v245
	v_fmac_f32_dpp v219, v43, v155 row_ror:1 row_mask:0xf bank_mask:0xf bound_ctrl:1
	v_rcp_f32_e32 v246, v246
	v_fmac_f32_dpp v220, v44, v156 row_ror:1 row_mask:0xf bank_mask:0xf bound_ctrl:1
	v_rcp_f32_e32 v247, v247
	v_fmac_f32_dpp v221, v45, v157 row_ror:1 row_mask:0xf bank_mask:0xf bound_ctrl:1
	v_rcp_f32_e32 v248, v248
	v_fmac_f32_dpp v222, v38, v158 row_ror:1 row_mask:0xf bank_mask:0xf bound_ctrl:1
	v_rcp_f32_e32 v249, v249
	v_fmac_f32_dpp v223, v39, v159 row_ror:1 row_mask:0xf bank_mask:0xf bound_ctrl:1
	v_pk_mul_f32 v[202:203], v[202:203], v[242:243]
	v_fmac_f32_dpp v224, v40, v160 row_ror:1 row_mask:0xf bank_mask:0xf bound_ctrl:1
	v_pk_mul_f32 v[204:205], v[204:205], v[244:245]
	v_fmac_f32_dpp v225, v41, v161 row_ror:1 row_mask:0xf bank_mask:0xf bound_ctrl:1
	v_pk_mul_f32 v[206:207], v[206:207], v[246:247]
	v_fmac_f32_dpp v218, v42, v182 row_ror:2 row_mask:0xf bank_mask:0xf bound_ctrl:1
	v_pk_mul_f32 v[226:227], v[226:227], v[248:249]
	v_fmac_f32_dpp v219, v43, v183 row_ror:2 row_mask:0xf bank_mask:0xf bound_ctrl:1
	v_pk_mul_f32 v[18:19], v[18:19], v[202:203]
	v_fmac_f32_dpp v220, v44, v184 row_ror:2 row_mask:0xf bank_mask:0xf bound_ctrl:1
	v_pk_mul_f32 v[20:21], v[20:21], v[204:205]
	v_fmac_f32_dpp v221, v45, v185 row_ror:2 row_mask:0xf bank_mask:0xf bound_ctrl:1
	v_pk_mul_f32 v[10:11], v[10:11], v[206:207]
	v_fmac_f32_dpp v222, v38, v190 row_ror:2 row_mask:0xf bank_mask:0xf bound_ctrl:1
	v_pk_mul_f32 v[12:13], v[12:13], v[226:227]
	v_fmac_f32_dpp v223, v39, v191 row_ror:2 row_mask:0xf bank_mask:0xf bound_ctrl:1
	v_cvt_pk_bf16_f32 v250, v18, v19
	v_fmac_f32_dpp v224, v40, v192 row_ror:2 row_mask:0xf bank_mask:0xf bound_ctrl:1
	v_cvt_pk_bf16_f32 v251, v20, v21
	v_fmac_f32_dpp v225, v41, v193 row_ror:2 row_mask:0xf bank_mask:0xf bound_ctrl:1
	v_cvt_pk_bf16_f32 v252, v10, v11
	v_cvt_pk_bf16_f32 v253, v12, v13
	global_store_dwordx4 v175, v[250:253], s[72:73]
	s_add_u32 s72, s84, 0xf2000
	s_addc_u32 s73, s85, 0
	v_pk_mul_f32 v[242:243], v[218:219], s[98:99]
	v_pk_mul_f32 v[244:245], v[220:221], s[98:99]
	v_pk_mul_f32 v[246:247], v[222:223], s[98:99]
	v_pk_mul_f32 v[248:249], v[224:225], s[98:99]
	v_exp_f32_e32 v242, v242
	v_exp_f32_e32 v243, v243
	v_exp_f32_e32 v244, v244
	v_exp_f32_e32 v245, v245
	v_exp_f32_e32 v246, v246
	v_exp_f32_e32 v247, v247
	v_exp_f32_e32 v248, v248
	v_exp_f32_e32 v249, v249
	v_pk_add_f32 v[242:243], v[242:243], s[92:93]
	v_pk_add_f32 v[244:245], v[244:245], s[92:93]
	v_pk_add_f32 v[246:247], v[246:247], s[92:93]
	v_pk_add_f32 v[248:249], v[248:249], s[92:93]
	v_rcp_f32_e32 v242, v242
	v_rcp_f32_e32 v243, v243
	v_rcp_f32_e32 v244, v244
	v_rcp_f32_e32 v245, v245
	v_rcp_f32_e32 v246, v246
	v_rcp_f32_e32 v247, v247
	v_rcp_f32_e32 v248, v248
	v_rcp_f32_e32 v249, v249
	v_pk_mul_f32 v[218:219], v[218:219], v[242:243]
	v_pk_mul_f32 v[220:221], v[220:221], v[244:245]
	v_pk_mul_f32 v[222:223], v[222:223], v[246:247]
	v_pk_mul_f32 v[224:225], v[224:225], v[248:249]
	v_pk_mul_f32 v[6:7], v[6:7], v[218:219]
	v_pk_mul_f32 v[8:9], v[8:9], v[220:221]
	v_pk_mul_f32 v[2:3], v[2:3], v[222:223]
	v_pk_mul_f32 v[4:5], v[4:5], v[224:225]
	v_cvt_pk_bf16_f32 v250, v6, v7
	v_cvt_pk_bf16_f32 v251, v8, v9
	v_cvt_pk_bf16_f32 v252, v2, v3
	v_cvt_pk_bf16_f32 v253, v4, v5
	global_store_dwordx4 v175, v[250:253], s[72:73]
	s_andn2_b64 vcc, exec, s[38:39]
	s_mov_b64 s[38:39], -1
	s_cbranch_vccnz .LBB0_239
	s_andn2_b64 vcc, exec, s[62:63]
	s_cbranch_vccnz .LBB0_238
	s_mov_b32 s52, 1
	s_branch .LBB0_238
